# accumulator zeroing with v_mov_b64; residual-epilogue row-sum exchanges via v_permlane16/32_swap instead of ds_bpermute
# speedup vs baseline: 1.0255x; 1.0025x over previous
.LBB0_521:
	s_add_i32 s50, s30, -2
	s_add_u32 s72, s72, 0x80
	s_addc_u32 s73, s73, 0
	s_add_u32 s78, s74, 0x100
	v_mov_b32_e32 v0, 0
	s_addc_u32 s79, s75, 0
	s_mov_b32 s74, 0
	v_mov_b32_e32 v1, v0
	v_mov_b64_e32 v[2:3], v[0:1]
	v_mov_b64_e32 v[4:5], v[0:1]
	v_mov_b64_e32 v[6:7], v[0:1]
	v_mov_b64_e32 v[8:9], v[0:1]
	v_mov_b64_e32 v[10:11], v[0:1]
	v_mov_b64_e32 v[12:13], v[0:1]
	v_mov_b64_e32 v[14:15], v[0:1]
	v_mov_b64_e32 v[16:17], v[0:1]
	v_mov_b64_e32 v[18:19], v[0:1]
	v_mov_b64_e32 v[20:21], v[0:1]
	v_mov_b64_e32 v[22:23], v[0:1]
	v_mov_b64_e32 v[24:25], v[0:1]
	v_mov_b64_e32 v[26:27], v[0:1]
	v_mov_b64_e32 v[28:29], v[0:1]
	v_mov_b64_e32 v[30:31], v[0:1]
	v_mov_b64_e32 v[32:33], v[0:1]
	v_mov_b64_e32 v[34:35], v[0:1]
	v_mov_b64_e32 v[36:37], v[0:1]
	v_mov_b64_e32 v[38:39], v[0:1]
	v_mov_b64_e32 v[40:41], v[0:1]
	v_mov_b64_e32 v[42:43], v[0:1]
	v_mov_b64_e32 v[44:45], v[0:1]
	v_mov_b64_e32 v[46:47], v[0:1]
	v_mov_b64_e32 v[48:49], v[0:1]
	v_mov_b64_e32 v[50:51], v[0:1]
	v_mov_b64_e32 v[52:53], v[0:1]
	v_mov_b64_e32 v[54:55], v[0:1]
	v_mov_b64_e32 v[56:57], v[0:1]
	v_mov_b64_e32 v[58:59], v[0:1]
	v_mov_b64_e32 v[60:61], v[0:1]
	v_mov_b64_e32 v[62:63], v[0:1]
	v_mov_b64_e32 v[64:65], v[0:1]
	v_mov_b64_e32 v[66:67], v[0:1]
	v_mov_b64_e32 v[68:69], v[0:1]
	v_mov_b64_e32 v[70:71], v[0:1]
	v_mov_b64_e32 v[72:73], v[0:1]
	v_mov_b64_e32 v[74:75], v[0:1]
	v_mov_b64_e32 v[76:77], v[0:1]
	v_mov_b64_e32 v[78:79], v[0:1]
	v_mov_b64_e32 v[80:81], v[0:1]
	v_mov_b64_e32 v[82:83], v[0:1]
	v_mov_b64_e32 v[84:85], v[0:1]
	v_mov_b64_e32 v[86:87], v[0:1]
	v_mov_b64_e32 v[88:89], v[0:1]
	v_mov_b64_e32 v[90:91], v[0:1]
	v_mov_b64_e32 v[92:93], v[0:1]
	v_mov_b64_e32 v[94:95], v[0:1]
	v_mov_b64_e32 v[96:97], v[0:1]
	v_mov_b64_e32 v[98:99], v[0:1]
	v_mov_b64_e32 v[100:101], v[0:1]
	v_mov_b64_e32 v[102:103], v[0:1]
	v_mov_b64_e32 v[104:105], v[0:1]
	v_mov_b64_e32 v[106:107], v[0:1]
	v_mov_b64_e32 v[108:109], v[0:1]
	v_mov_b64_e32 v[110:111], v[0:1]
	v_mov_b64_e32 v[112:113], v[0:1]
	v_mov_b64_e32 v[114:115], v[0:1]
	v_mov_b64_e32 v[116:117], v[0:1]
	v_mov_b64_e32 v[118:119], v[0:1]
	v_mov_b64_e32 v[120:121], v[0:1]
	v_mov_b64_e32 v[122:123], v[0:1]
	v_mov_b64_e32 v[124:125], v[0:1]
	v_mov_b64_e32 v[126:127], v[0:1]
.LBB0_522:
	s_add_i32 vcc_lo, s74, 2
	s_add_u32 s76, s72, 0x80
	s_addc_u32 s75, s73, 0
	s_add_i32 vcc_hi, 0, 0x10000
	v_add_u32_e32 v140, vcc_hi, v237
	s_waitcnt lgkmcnt(0)
	ds_read_b128 v[128:131], v140
	ds_read_b128 v[132:135], v140 offset:1024
	ds_read_b128 v[136:139], v140 offset:2048
	ds_read_b128 v[140:143], v140 offset:3072
	s_cmp_eq_u32 s50, s74
	s_cselect_b32 s74, s68, s76
	s_cselect_b32 s75, s69, s75
	s_cselect_b32 s77, s71, s79
	s_cselect_b32 s76, s70, s78
	v_lshl_add_u64 v[176:177], s[72:73], 0, v[206:207]
	s_add_i32 m0, s93, 0xc000
	ds_read_b128 v[144:147], v240
	ds_read_b128 v[148:151], v240 offset:1024
	ds_read_b128 v[152:155], v240 offset:2048
	ds_read_b128 v[156:159], v240 offset:3072
	ds_read_b128 v[160:163], v240 offset:4096
	ds_read_b128 v[164:167], v240 offset:5120
	ds_read_b128 v[168:171], v240 offset:6144
	ds_read_b128 v[172:175], v240 offset:7168
	global_load_lds_dwordx4 v[176:177], off
	v_lshl_add_u64 v[176:177], s[72:73], 0, v[208:209]
	s_add_i32 m0, s93, 0xe000
	s_nop 0
	global_load_lds_dwordx4 v[176:177], off
	s_waitcnt lgkmcnt(8)
	s_barrier
	s_waitcnt lgkmcnt(0)
	v_mfma_f32_16x16x32_bf16 v[124:127], v[128:131], v[144:147], v[124:127]
	v_mfma_f32_16x16x32_bf16 v[120:123], v[136:139], v[144:147], v[120:123]
	v_mfma_f32_16x16x32_bf16 v[116:119], v[128:131], v[152:155], v[116:119]
	v_mfma_f32_16x16x32_bf16 v[112:115], v[136:139], v[152:155], v[112:115]
	v_mfma_f32_16x16x32_bf16 v[100:103], v[128:131], v[160:163], v[100:103]
	v_mfma_f32_16x16x32_bf16 v[96:99], v[136:139], v[160:163], v[96:99]
	v_mfma_f32_16x16x32_bf16 v[84:87], v[128:131], v[168:171], v[84:87]
	v_mfma_f32_16x16x32_bf16 v[80:83], v[136:139], v[168:171], v[80:83]
	v_mfma_f32_16x16x32_bf16 v[124:127], v[132:135], v[148:151], v[124:127]
	v_mfma_f32_16x16x32_bf16 v[120:123], v[140:143], v[148:151], v[120:123]
	v_mfma_f32_16x16x32_bf16 v[116:119], v[132:135], v[156:159], v[116:119]
	v_mfma_f32_16x16x32_bf16 v[112:115], v[140:143], v[156:159], v[112:115]
	v_mfma_f32_16x16x32_bf16 v[100:103], v[132:135], v[164:167], v[100:103]
	v_mfma_f32_16x16x32_bf16 v[96:99], v[140:143], v[164:167], v[96:99]
	v_mfma_f32_16x16x32_bf16 v[84:87], v[132:135], v[172:175], v[84:87]
	v_mfma_f32_16x16x32_bf16 v[80:83], v[140:143], v[172:175], v[80:83]
	s_barrier
	s_add_i32 s31, 0, 0x14000
	s_add_i32 vcc_hi, vcc_hi, s87
	v_add_u32_e32 v188, s31, v237
	v_lshl_add_u64 v[210:211], s[76:77], 0, v[196:197]
	s_mov_b32 m0, vcc_hi
	ds_read_b128 v[176:179], v188
	ds_read_b128 v[180:183], v188 offset:1024
	ds_read_b128 v[184:187], v188 offset:2048
	ds_read_b128 v[188:191], v188 offset:3072
	global_load_lds_dwordx4 v[210:211], off
	v_lshl_add_u64 v[212:213], s[76:77], 0, v[200:201]
	s_add_i32 m0, vcc_hi, 0x2000
	s_nop 0
	global_load_lds_dwordx4 v[212:213], off
	s_barrier
	s_waitcnt lgkmcnt(0)
	v_mfma_f32_16x16x32_bf16 v[108:111], v[176:179], v[144:147], v[108:111]
	v_mfma_f32_16x16x32_bf16 v[104:107], v[184:187], v[144:147], v[104:107]
	v_mfma_f32_16x16x32_bf16 v[92:95], v[176:179], v[152:155], v[92:95]
	v_mfma_f32_16x16x32_bf16 v[88:91], v[184:187], v[152:155], v[88:91]
	v_mfma_f32_16x16x32_bf16 v[76:79], v[176:179], v[160:163], v[76:79]
	v_mfma_f32_16x16x32_bf16 v[72:75], v[184:187], v[160:163], v[72:75]
	v_mfma_f32_16x16x32_bf16 v[68:71], v[176:179], v[168:171], v[68:71]
	v_mfma_f32_16x16x32_bf16 v[64:67], v[184:187], v[168:171], v[64:67]
	v_mfma_f32_16x16x32_bf16 v[108:111], v[180:183], v[148:151], v[108:111]
	v_mfma_f32_16x16x32_bf16 v[104:107], v[188:191], v[148:151], v[104:107]
	v_mfma_f32_16x16x32_bf16 v[92:95], v[180:183], v[156:159], v[92:95]
	v_mfma_f32_16x16x32_bf16 v[88:91], v[188:191], v[156:159], v[88:91]
	v_mfma_f32_16x16x32_bf16 v[76:79], v[180:183], v[164:167], v[76:79]
	v_mfma_f32_16x16x32_bf16 v[72:75], v[188:191], v[164:167], v[72:75]
	v_mfma_f32_16x16x32_bf16 v[68:71], v[180:183], v[172:175], v[68:71]
	v_mfma_f32_16x16x32_bf16 v[64:67], v[188:191], v[172:175], v[64:67]
	s_mov_b32 m0, s93
	v_lshl_add_u64 v[214:215], s[74:75], 0, v[194:195]
	s_barrier
	ds_read_b128 v[144:147], v240 offset:16384
	ds_read_b128 v[148:151], v240 offset:17408
	ds_read_b128 v[152:155], v240 offset:18432
	ds_read_b128 v[156:159], v240 offset:19456
	ds_read_b128 v[160:163], v240 offset:20480
	ds_read_b128 v[164:167], v240 offset:21504
	ds_read_b128 v[168:171], v240 offset:22528
	ds_read_b128 v[172:175], v240 offset:23552
	global_load_lds_dwordx4 v[214:215], off
	v_lshl_add_u64 v[216:217], s[74:75], 0, v[198:199]
	s_mov_b32 m0, s54
	s_nop 0
	global_load_lds_dwordx4 v[216:217], off
	s_barrier
	s_waitcnt lgkmcnt(0)
	v_mfma_f32_16x16x32_bf16 v[60:63], v[128:131], v[144:147], v[60:63]
	v_mfma_f32_16x16x32_bf16 v[56:59], v[136:139], v[144:147], v[56:59]
	v_mfma_f32_16x16x32_bf16 v[52:55], v[128:131], v[152:155], v[52:55]
	v_mfma_f32_16x16x32_bf16 v[48:51], v[136:139], v[152:155], v[48:51]
	v_mfma_f32_16x16x32_bf16 v[36:39], v[128:131], v[160:163], v[36:39]
	v_mfma_f32_16x16x32_bf16 v[32:35], v[136:139], v[160:163], v[32:35]
	v_mfma_f32_16x16x32_bf16 v[20:23], v[128:131], v[168:171], v[20:23]
	v_mfma_f32_16x16x32_bf16 v[16:19], v[136:139], v[168:171], v[16:19]
	v_mfma_f32_16x16x32_bf16 v[60:63], v[132:135], v[148:151], v[60:63]
	v_mfma_f32_16x16x32_bf16 v[56:59], v[140:143], v[148:151], v[56:59]
	v_mfma_f32_16x16x32_bf16 v[52:55], v[132:135], v[156:159], v[52:55]
	v_mfma_f32_16x16x32_bf16 v[48:51], v[140:143], v[156:159], v[48:51]
	v_mfma_f32_16x16x32_bf16 v[36:39], v[132:135], v[164:167], v[36:39]
	v_mfma_f32_16x16x32_bf16 v[32:35], v[140:143], v[164:167], v[32:35]
	v_mfma_f32_16x16x32_bf16 v[20:23], v[132:135], v[172:175], v[20:23]
	v_mfma_f32_16x16x32_bf16 v[16:19], v[140:143], v[172:175], v[16:19]
	s_barrier
	s_add_u32 s76, s76, s20
	s_addc_u32 s77, s77, 0
	s_add_i32 s31, s31, s87
	v_lshl_add_u64 v[218:219], s[76:77], 0, v[196:197]
	s_mov_b32 m0, s31
	v_lshl_add_u64 v[220:221], s[76:77], 0, v[200:201]
	global_load_lds_dwordx4 v[218:219], off
	s_add_i32 m0, s31, 0x2000
	s_nop 0
	global_load_lds_dwordx4 v[220:221], off
	s_waitcnt vmcnt(6)
	s_barrier
	v_mfma_f32_16x16x32_bf16 v[44:47], v[176:179], v[144:147], v[44:47]
	v_mfma_f32_16x16x32_bf16 v[40:43], v[184:187], v[144:147], v[40:43]
	v_mfma_f32_16x16x32_bf16 v[28:31], v[176:179], v[152:155], v[28:31]
	v_mfma_f32_16x16x32_bf16 v[24:27], v[184:187], v[152:155], v[24:27]
	v_mfma_f32_16x16x32_bf16 v[12:15], v[176:179], v[160:163], v[12:15]
	v_mfma_f32_16x16x32_bf16 v[8:11], v[184:187], v[160:163], v[8:11]
	v_mfma_f32_16x16x32_bf16 v[4:7], v[176:179], v[168:171], v[4:7]
	v_mfma_f32_16x16x32_bf16 v[0:3], v[184:187], v[168:171], v[0:3]
	v_mfma_f32_16x16x32_bf16 v[44:47], v[180:183], v[148:151], v[44:47]
	v_mfma_f32_16x16x32_bf16 v[40:43], v[188:191], v[148:151], v[40:43]
	v_mfma_f32_16x16x32_bf16 v[28:31], v[180:183], v[156:159], v[28:31]
	v_mfma_f32_16x16x32_bf16 v[24:27], v[188:191], v[156:159], v[24:27]
	v_mfma_f32_16x16x32_bf16 v[12:15], v[180:183], v[164:167], v[12:15]
	v_mfma_f32_16x16x32_bf16 v[8:11], v[188:191], v[164:167], v[8:11]
	v_mfma_f32_16x16x32_bf16 v[4:7], v[180:183], v[172:175], v[4:7]
	v_mfma_f32_16x16x32_bf16 v[0:3], v[188:191], v[172:175], v[0:3]
	s_add_i32 s31, 0, 0x18000
	v_add_u32_e32 v140, s31, v237
	s_barrier
	ds_read_b128 v[128:131], v140
	ds_read_b128 v[132:135], v140 offset:1024
	ds_read_b128 v[136:139], v140 offset:2048
	ds_read_b128 v[140:143], v140 offset:3072
	s_add_u32 s74, s74, s20
	s_addc_u32 s75, s75, 0
	s_mov_b32 m0, s34
	v_lshl_add_u64 v[176:177], s[74:75], 0, v[194:195]
	ds_read_b128 v[144:147], v240 offset:32768
	ds_read_b128 v[148:151], v240 offset:33792
	ds_read_b128 v[152:155], v240 offset:34816
	ds_read_b128 v[156:159], v240 offset:35840
	ds_read_b128 v[160:163], v240 offset:36864
	ds_read_b128 v[164:167], v240 offset:37888
	ds_read_b128 v[168:171], v240 offset:38912
	ds_read_b128 v[172:175], v240 offset:39936
	global_load_lds_dwordx4 v[176:177], off
	v_lshl_add_u64 v[176:177], s[74:75], 0, v[198:199]
	s_mov_b32 m0, s35
	s_nop 0
	global_load_lds_dwordx4 v[176:177], off
	s_waitcnt lgkmcnt(8)
	s_barrier
	s_waitcnt lgkmcnt(0)
	v_mfma_f32_16x16x32_bf16 v[124:127], v[128:131], v[144:147], v[124:127]
	v_mfma_f32_16x16x32_bf16 v[120:123], v[136:139], v[144:147], v[120:123]
	v_mfma_f32_16x16x32_bf16 v[116:119], v[128:131], v[152:155], v[116:119]
	v_mfma_f32_16x16x32_bf16 v[112:115], v[136:139], v[152:155], v[112:115]
	v_mfma_f32_16x16x32_bf16 v[100:103], v[128:131], v[160:163], v[100:103]
	v_mfma_f32_16x16x32_bf16 v[96:99], v[136:139], v[160:163], v[96:99]
	v_mfma_f32_16x16x32_bf16 v[84:87], v[128:131], v[168:171], v[84:87]
	v_mfma_f32_16x16x32_bf16 v[80:83], v[136:139], v[168:171], v[80:83]
	v_mfma_f32_16x16x32_bf16 v[124:127], v[132:135], v[148:151], v[124:127]
	v_mfma_f32_16x16x32_bf16 v[120:123], v[140:143], v[148:151], v[120:123]
	v_mfma_f32_16x16x32_bf16 v[116:119], v[132:135], v[156:159], v[116:119]
	v_mfma_f32_16x16x32_bf16 v[112:115], v[140:143], v[156:159], v[112:115]
	v_mfma_f32_16x16x32_bf16 v[100:103], v[132:135], v[164:167], v[100:103]
	v_mfma_f32_16x16x32_bf16 v[96:99], v[140:143], v[164:167], v[96:99]
	v_mfma_f32_16x16x32_bf16 v[84:87], v[132:135], v[172:175], v[84:87]
	v_mfma_f32_16x16x32_bf16 v[80:83], v[140:143], v[172:175], v[80:83]
	s_barrier
	s_add_i32 s74, 0, 0x1c000
	s_add_i32 s31, s31, s87
	v_add_u32_e32 v188, s74, v237
	v_lshl_add_u64 v[210:211], v[210:211], 0, s[60:61]
	s_mov_b32 m0, s31
	ds_read_b128 v[176:179], v188
	ds_read_b128 v[180:183], v188 offset:1024
	ds_read_b128 v[184:187], v188 offset:2048
	ds_read_b128 v[188:191], v188 offset:3072
	global_load_lds_dwordx4 v[210:211], off
	v_lshl_add_u64 v[210:211], v[212:213], 0, s[60:61]
	s_add_i32 m0, s31, 0x2000
	s_nop 0
	global_load_lds_dwordx4 v[210:211], off
	s_barrier
	s_waitcnt lgkmcnt(0)
	v_mfma_f32_16x16x32_bf16 v[108:111], v[176:179], v[144:147], v[108:111]
	v_mfma_f32_16x16x32_bf16 v[104:107], v[184:187], v[144:147], v[104:107]
	v_mfma_f32_16x16x32_bf16 v[92:95], v[176:179], v[152:155], v[92:95]
	v_mfma_f32_16x16x32_bf16 v[88:91], v[184:187], v[152:155], v[88:91]
	v_mfma_f32_16x16x32_bf16 v[76:79], v[176:179], v[160:163], v[76:79]
	v_mfma_f32_16x16x32_bf16 v[72:75], v[184:187], v[160:163], v[72:75]
	v_mfma_f32_16x16x32_bf16 v[68:71], v[176:179], v[168:171], v[68:71]
	v_mfma_f32_16x16x32_bf16 v[64:67], v[184:187], v[168:171], v[64:67]
	v_mfma_f32_16x16x32_bf16 v[108:111], v[180:183], v[148:151], v[108:111]
	v_mfma_f32_16x16x32_bf16 v[104:107], v[188:191], v[148:151], v[104:107]
	v_mfma_f32_16x16x32_bf16 v[92:95], v[180:183], v[156:159], v[92:95]
	v_mfma_f32_16x16x32_bf16 v[88:91], v[188:191], v[156:159], v[88:91]
	v_mfma_f32_16x16x32_bf16 v[76:79], v[180:183], v[164:167], v[76:79]
	v_mfma_f32_16x16x32_bf16 v[72:75], v[188:191], v[164:167], v[72:75]
	v_mfma_f32_16x16x32_bf16 v[68:71], v[180:183], v[172:175], v[68:71]
	v_mfma_f32_16x16x32_bf16 v[64:67], v[188:191], v[172:175], v[64:67]
	s_mov_b32 m0, s97
	v_lshl_add_u64 v[210:211], v[214:215], 0, s[60:61]
	s_barrier
	ds_read_b128 v[144:147], v240 offset:49152
	ds_read_b128 v[148:151], v240 offset:50176
	ds_read_b128 v[152:155], v240 offset:51200
	ds_read_b128 v[156:159], v240 offset:52224
	ds_read_b128 v[160:163], v240 offset:53248
	ds_read_b128 v[164:167], v240 offset:54272
	ds_read_b128 v[168:171], v240 offset:55296
	ds_read_b128 v[172:175], v240 offset:56320
	global_load_lds_dwordx4 v[210:211], off
	v_lshl_add_u64 v[210:211], v[216:217], 0, s[60:61]
	s_mov_b32 m0, s36
	s_nop 0
	global_load_lds_dwordx4 v[210:211], off
	s_barrier
	s_waitcnt lgkmcnt(0)
	v_mfma_f32_16x16x32_bf16 v[60:63], v[128:131], v[144:147], v[60:63]
	v_mfma_f32_16x16x32_bf16 v[56:59], v[136:139], v[144:147], v[56:59]
	v_mfma_f32_16x16x32_bf16 v[52:55], v[128:131], v[152:155], v[52:55]
	v_mfma_f32_16x16x32_bf16 v[48:51], v[136:139], v[152:155], v[48:51]
	v_mfma_f32_16x16x32_bf16 v[36:39], v[128:131], v[160:163], v[36:39]
	v_mfma_f32_16x16x32_bf16 v[32:35], v[136:139], v[160:163], v[32:35]
	v_mfma_f32_16x16x32_bf16 v[20:23], v[128:131], v[168:171], v[20:23]
	v_mfma_f32_16x16x32_bf16 v[16:19], v[136:139], v[168:171], v[16:19]
	v_mfma_f32_16x16x32_bf16 v[60:63], v[132:135], v[148:151], v[60:63]
	v_mfma_f32_16x16x32_bf16 v[56:59], v[140:143], v[148:151], v[56:59]
	v_mfma_f32_16x16x32_bf16 v[52:55], v[132:135], v[156:159], v[52:55]
	v_mfma_f32_16x16x32_bf16 v[48:51], v[140:143], v[156:159], v[48:51]
	v_mfma_f32_16x16x32_bf16 v[36:39], v[132:135], v[164:167], v[36:39]
	v_mfma_f32_16x16x32_bf16 v[32:35], v[140:143], v[164:167], v[32:35]
	v_mfma_f32_16x16x32_bf16 v[20:23], v[132:135], v[172:175], v[20:23]
	v_mfma_f32_16x16x32_bf16 v[16:19], v[140:143], v[172:175], v[16:19]
	s_barrier
	s_add_i32 s31, s74, s87
	v_lshl_add_u64 v[128:129], v[218:219], 0, s[60:61]
	s_mov_b32 m0, s31
	s_nop 0
	global_load_lds_dwordx4 v[128:129], off
	v_lshl_add_u64 v[128:129], v[220:221], 0, s[60:61]
	s_add_i32 m0, s31, 0x2000
	s_nop 0
	global_load_lds_dwordx4 v[128:129], off
	s_waitcnt vmcnt(6)
	s_barrier
	v_mfma_f32_16x16x32_bf16 v[44:47], v[176:179], v[144:147], v[44:47]
	v_mfma_f32_16x16x32_bf16 v[40:43], v[184:187], v[144:147], v[40:43]
	v_mfma_f32_16x16x32_bf16 v[28:31], v[176:179], v[152:155], v[28:31]
	v_mfma_f32_16x16x32_bf16 v[24:27], v[184:187], v[152:155], v[24:27]
	v_mfma_f32_16x16x32_bf16 v[12:15], v[176:179], v[160:163], v[12:15]
	v_mfma_f32_16x16x32_bf16 v[8:11], v[184:187], v[160:163], v[8:11]
	v_mfma_f32_16x16x32_bf16 v[4:7], v[176:179], v[168:171], v[4:7]
	v_mfma_f32_16x16x32_bf16 v[0:3], v[184:187], v[168:171], v[0:3]
	v_mfma_f32_16x16x32_bf16 v[44:47], v[180:183], v[148:151], v[44:47]
	v_mfma_f32_16x16x32_bf16 v[40:43], v[188:191], v[148:151], v[40:43]
	v_mfma_f32_16x16x32_bf16 v[28:31], v[180:183], v[156:159], v[28:31]
	v_mfma_f32_16x16x32_bf16 v[24:27], v[188:191], v[156:159], v[24:27]
	v_mfma_f32_16x16x32_bf16 v[12:15], v[180:183], v[164:167], v[12:15]
	v_mfma_f32_16x16x32_bf16 v[8:11], v[188:191], v[164:167], v[8:11]
	v_mfma_f32_16x16x32_bf16 v[4:7], v[180:183], v[172:175], v[4:7]
	v_mfma_f32_16x16x32_bf16 v[0:3], v[188:191], v[172:175], v[0:3]
	s_add_u32 s72, s72, 0x100
	s_addc_u32 s73, s73, 0
	s_add_u32 s78, s78, 0x100
	s_addc_u32 s79, s79, 0
	s_cmp_ge_u32 vcc_lo, s30
	s_mov_b32 s74, vcc_lo
	s_barrier
	s_cbranch_scc0 .LBB0_522
	s_cmp_lt_i32 s91, 0
	s_mov_b64 s[72:73], -1
	s_cbranch_scc0 .LBB0_716
	s_lshl_b32 s78, s46, 8
	s_cmp_lt_i32 s81, 2
	s_cbranch_scc1 .LBB0_582
	s_cmp_lt_i32 s81, 3
	s_cbranch_scc1 .LBB0_579
	s_cmp_lg_u32 s81, 3
	s_cbranch_scc0 .LBB0_544
	v_lshl_or_b32 v128, s19, 7, v238
	v_ashrrev_i32_e32 v129, 31, v128
	v_lshl_add_u64 v[144:145], v[128:129], 1, s[24:25]
	v_and_b32_e32 v129, 64, v231
	v_xor_b32_e32 v128, 16, v231
	v_add_u32_e32 v129, 64, v129
	v_cmp_lt_i32_e32 vcc, v128, v129
	v_add_u32_e32 v146, s78, v202
	v_ashrrev_i32_e32 v147, 31, v146
	v_cndmask_b32_e32 v128, v231, v128, vcc
	v_lshlrev_b32_e32 v167, 2, v128
	v_xor_b32_e32 v128, 32, v231
	v_cmp_lt_i32_e32 vcc, v128, v129
	v_or_b32_e32 v156, 16, v146
	v_ashrrev_i32_e32 v157, 31, v156
	v_cndmask_b32_e32 v128, v231, v128, vcc
	v_lshlrev_b32_e32 v166, 2, v128
	v_lshlrev_b64 v[128:129], 12, v[146:147]
	v_lshl_add_u64 v[160:161], v[144:145], 0, v[128:129]
	global_load_dwordx4 v[140:143], v[160:161], off
	v_or_b32_e32 v152, 32, v146
	v_lshlrev_b64 v[128:129], 12, v[156:157]
	v_ashrrev_i32_e32 v153, 31, v152
	v_or_b32_e32 v148, 48, v146
	v_lshl_add_u64 v[158:159], v[144:145], 0, v[128:129]
	v_lshlrev_b64 v[128:129], 12, v[152:153]
	v_ashrrev_i32_e32 v149, 31, v148
	v_lshl_add_u64 v[154:155], v[144:145], 0, v[128:129]
	v_lshlrev_b64 v[128:129], 12, v[148:149]
	v_lshl_add_u64 v[150:151], v[144:145], 0, v[128:129]
	global_load_dwordx4 v[136:139], v[158:159], off
	global_load_dwordx4 v[132:135], v[154:155], off
	global_load_dwordx4 v[128:131], v[150:151], off
	v_mul_f32_e32 v163, 0xbfb8aa3b, v104
	v_exp_f32_e32 v163, v163
	v_mul_f32_e32 v162, 0xbfb8aa3b, v108
	v_exp_f32_e32 v162, v162
	v_add_f32_e32 v163, 1.0, v163
	v_rcp_f32_e32 v164, v163
	v_mul_f32_e32 v163, 0xbfb8aa3b, v109
	v_exp_f32_e32 v163, v163
	v_add_f32_e32 v162, 1.0, v162
	v_rcp_f32_e32 v162, v162
	v_add_f32_e32 v163, 1.0, v163
	v_rcp_f32_e32 v163, v163
	s_waitcnt vmcnt(0)
	v_lshlrev_b32_e32 v168, 16, v140
	v_and_b32_e32 v169, 0xffff0000, v140
	v_mul_f32_e32 v140, 0xbfb8aa3b, v105
	v_exp_f32_e32 v140, v140
	v_pk_fma_f32 v[162:163], v[162:163], v[124:125], v[168:169]
	v_lshlrev_b32_e32 v168, 16, v142
	v_and_b32_e32 v169, 0xffff0000, v142
	v_add_f32_e32 v140, 1.0, v140
	v_rcp_f32_e32 v165, v140
	v_mul_f32_e32 v140, 0xbfb8aa3b, v110
	v_exp_f32_e32 v140, v140
	v_mul_f32_e32 v142, 0xbfb8aa3b, v111
	v_pk_fma_f32 v[164:165], v[164:165], v[120:121], v[168:169]
	v_lshlrev_b32_e32 v170, 16, v141
	v_add_f32_e32 v140, 1.0, v140
	v_rcp_f32_e32 v168, v140
	v_mul_f32_e32 v140, 0xbfb8aa3b, v106
	v_and_b32_e32 v171, 0xffff0000, v141
	v_mul_f32_e32 v141, 0xbfb8aa3b, v107
	v_exp_f32_e32 v140, v140
	v_exp_f32_e32 v142, v142
	v_exp_f32_e32 v141, v141
	v_add_f32_e32 v140, 1.0, v140
	v_add_f32_e32 v142, 1.0, v142
	v_add_f32_e32 v141, 1.0, v141
	v_rcp_f32_e32 v140, v140
	v_rcp_f32_e32 v169, v142
	v_rcp_f32_e32 v141, v141
	v_lshlrev_b32_e32 v142, 16, v143
	v_and_b32_e32 v143, 0xffff0000, v143
	v_pk_fma_f32 v[168:169], v[168:169], v[126:127], v[170:171]
	v_pk_fma_f32 v[170:171], v[140:141], v[122:123], v[142:143]
	v_cvt_pk_bf16_f32 v140, v162, v163
	v_cvt_pk_bf16_f32 v141, v168, v169
	v_cvt_pk_bf16_f32 v142, v164, v165
	v_cvt_pk_bf16_f32 v143, v170, v171
	global_store_dwordx4 v[160:161], v[140:143], off
	v_pk_mul_f32 v[160:161], v[164:165], v[164:165]
	s_nop 0
	v_pk_mul_f32 v[140:141], v[162:163], v[162:163]
	v_pk_mul_f32 v[142:143], v[168:169], v[168:169]
	v_add_f32_e32 v140, v140, v141
	v_add_f32_e32 v142, v142, v143
	v_pk_mul_f32 v[162:163], v[170:171], v[170:171]
	v_add_f32_e32 v140, v140, v142
	v_add_f32_e32 v141, v160, v161
	v_add_f32_e32 v162, v162, v163
	v_add_f32_e32 v140, v141, v140
	v_add_f32_e32 v140, v162, v140
	v_mov_b32_e32 v141, v140
	s_nop 1
	v_permlane16_swap_b32_e32 v141, v140
	s_waitcnt lgkmcnt(0)
	v_add_f32_e32 v140, v140, v141
	v_mov_b32_e32 v141, v140
	s_nop 1
	v_permlane32_swap_b32_e32 v141, v140
	s_and_saveexec_b64 s[72:73], s[6:7]
	s_cbranch_execz .LBB0_529
	s_waitcnt lgkmcnt(0)
	v_add_f32_e32 v142, v140, v141
	s_lshl_b32 s74, s19, 2
	v_lshlrev_b64 v[140:141], 8, v[146:147]
	s_ashr_i32 s75, s74, 31
	v_lshl_add_u64 v[140:141], s[26:27], 0, v[140:141]
	v_lshl_add_u64 v[140:141], s[74:75], 2, v[140:141]
	s_lshl_b32 s50, s37, 2
	v_lshl_add_u64 v[140:141], v[140:141], 0, s[50:51]
	global_store_dword v[140:141], v142, off
.LBB0_529:
	s_or_b64 exec, exec, s[72:73]
	v_mul_f32_e32 v147, 0xbfb8aa3b, v92
	v_exp_f32_e32 v147, v147
	v_lshlrev_b32_e32 v140, 16, v136
	s_waitcnt lgkmcnt(0)
	v_and_b32_e32 v141, 0xffff0000, v136
	v_lshlrev_b32_e32 v142, 16, v138
	v_add_f32_e32 v147, 1.0, v147
	v_rcp_f32_e32 v160, v147
	v_mul_f32_e32 v147, 0xbfb8aa3b, v88
	v_exp_f32_e32 v147, v147
	v_and_b32_e32 v143, 0xffff0000, v138
	v_lshlrev_b32_e32 v136, 16, v137
	v_and_b32_e32 v137, 0xffff0000, v137
	v_add_f32_e32 v147, 1.0, v147
	v_rcp_f32_e32 v162, v147
	v_mul_f32_e32 v147, 0xbfb8aa3b, v93
	v_exp_f32_e32 v147, v147
	v_lshlrev_b32_e32 v138, 16, v139
	v_and_b32_e32 v139, 0xffff0000, v139
	v_add_f32_e32 v147, 1.0, v147
	v_rcp_f32_e32 v161, v147
	v_mul_f32_e32 v147, 0xbfb8aa3b, v89
	v_exp_f32_e32 v147, v147
	v_pk_fma_f32 v[140:141], v[160:161], v[116:117], v[140:141]
	v_add_f32_e32 v147, 1.0, v147
	v_rcp_f32_e32 v163, v147
	v_mul_f32_e32 v147, 0xbfb8aa3b, v94
	v_exp_f32_e32 v147, v147
	v_pk_fma_f32 v[142:143], v[162:163], v[112:113], v[142:143]
	v_add_f32_e32 v147, 1.0, v147
	v_rcp_f32_e32 v160, v147
	v_mul_f32_e32 v147, 0xbfb8aa3b, v90
	v_exp_f32_e32 v147, v147
	s_nop 0
	v_add_f32_e32 v147, 1.0, v147
	v_rcp_f32_e32 v162, v147
	v_mul_f32_e32 v147, 0xbfb8aa3b, v95
	v_exp_f32_e32 v147, v147
	s_nop 0
	v_add_f32_e32 v147, 1.0, v147
	v_rcp_f32_e32 v161, v147
	s_nop 0
	v_pk_fma_f32 v[160:161], v[160:161], v[118:119], v[136:137]
	v_mul_f32_e32 v136, 0xbfb8aa3b, v91
	v_exp_f32_e32 v136, v136
	v_cvt_pk_bf16_f32 v137, v160, v161
	v_add_f32_e32 v136, 1.0, v136
	v_rcp_f32_e32 v163, v136
	v_cvt_pk_bf16_f32 v136, v140, v141
	v_pk_fma_f32 v[162:163], v[162:163], v[114:115], v[138:139]
	v_cvt_pk_bf16_f32 v138, v142, v143
	v_cvt_pk_bf16_f32 v139, v162, v163
	global_store_dwordx4 v[158:159], v[136:139], off
	s_nop 1
	v_pk_mul_f32 v[136:137], v[140:141], v[140:141]
	v_pk_mul_f32 v[138:139], v[160:161], v[160:161]
	v_pk_mul_f32 v[140:141], v[142:143], v[142:143]
	v_add_f32_e32 v138, v138, v139
	v_add_f32_e32 v136, v136, v137
	v_pk_mul_f32 v[142:143], v[162:163], v[162:163]
	v_add_f32_e32 v136, v136, v138
	v_add_f32_e32 v137, v140, v141
	v_add_f32_e32 v136, v137, v136
	v_add_f32_e32 v137, v142, v143
	v_add_f32_e32 v136, v137, v136
	v_mov_b32_e32 v137, v136
	s_nop 1
	v_permlane16_swap_b32_e32 v137, v136
	s_waitcnt lgkmcnt(0)
	v_add_f32_e32 v136, v136, v137
	v_mov_b32_e32 v137, v136
	s_nop 1
	v_permlane32_swap_b32_e32 v137, v136
	s_and_saveexec_b64 s[72:73], s[6:7]
	s_cbranch_execz .LBB0_531
	s_waitcnt lgkmcnt(0)
	v_add_f32_e32 v138, v136, v137
	s_lshl_b32 s74, s19, 2
	v_lshlrev_b64 v[136:137], 8, v[156:157]
	s_ashr_i32 s75, s74, 31
	v_lshl_add_u64 v[136:137], s[26:27], 0, v[136:137]
	v_lshl_add_u64 v[136:137], s[74:75], 2, v[136:137]
	s_lshl_b32 s50, s37, 2
	v_lshl_add_u64 v[136:137], v[136:137], 0, s[50:51]
	global_store_dword v[136:137], v138, off
.LBB0_531:
	s_or_b64 exec, exec, s[72:73]
	v_mul_f32_e32 v141, 0xbfb8aa3b, v72
	v_exp_f32_e32 v141, v141
	v_mul_f32_e32 v140, 0xbfb8aa3b, v76
	v_exp_f32_e32 v140, v140
	v_lshlrev_b32_e32 v136, 16, v132
	v_add_f32_e32 v141, 1.0, v141
	v_rcp_f32_e32 v142, v141
	v_mul_f32_e32 v141, 0xbfb8aa3b, v77
	v_exp_f32_e32 v141, v141
	v_add_f32_e32 v140, 1.0, v140
	v_rcp_f32_e32 v140, v140
	s_waitcnt lgkmcnt(0)
	v_and_b32_e32 v137, 0xffff0000, v132
	v_add_f32_e32 v141, 1.0, v141
	v_rcp_f32_e32 v141, v141
	v_lshlrev_b32_e32 v138, 16, v134
	v_and_b32_e32 v139, 0xffff0000, v134
	v_lshlrev_b32_e32 v132, 16, v133
	v_pk_fma_f32 v[136:137], v[140:141], v[100:101], v[136:137]
	v_mul_f32_e32 v140, 0xbfb8aa3b, v73
	v_exp_f32_e32 v140, v140
	v_mul_f32_e32 v141, 0xbfb8aa3b, v74
	v_exp_f32_e32 v141, v141
	v_and_b32_e32 v133, 0xffff0000, v133
	v_add_f32_e32 v140, 1.0, v140
	v_rcp_f32_e32 v143, v140
	v_add_f32_e32 v141, 1.0, v141
	v_mul_f32_e32 v140, 0xbfb8aa3b, v78
	v_exp_f32_e32 v140, v140
	v_pk_fma_f32 v[138:139], v[142:143], v[96:97], v[138:139]
	v_rcp_f32_e32 v142, v141
	v_mul_f32_e32 v141, 0xbfb8aa3b, v79
	v_exp_f32_e32 v141, v141
	v_add_f32_e32 v140, 1.0, v140
	v_rcp_f32_e32 v140, v140
	v_lshlrev_b32_e32 v134, 16, v135
	v_add_f32_e32 v141, 1.0, v141
	v_rcp_f32_e32 v141, v141
	v_and_b32_e32 v135, 0xffff0000, v135
	v_pk_fma_f32 v[140:141], v[140:141], v[102:103], v[132:133]
	v_mul_f32_e32 v132, 0xbfb8aa3b, v75
	v_exp_f32_e32 v132, v132
	v_cvt_pk_bf16_f32 v133, v140, v141
	v_add_f32_e32 v132, 1.0, v132
	v_rcp_f32_e32 v143, v132
	v_cvt_pk_bf16_f32 v132, v136, v137
	v_pk_fma_f32 v[142:143], v[142:143], v[98:99], v[134:135]
	v_cvt_pk_bf16_f32 v134, v138, v139
	v_cvt_pk_bf16_f32 v135, v142, v143
	global_store_dwordx4 v[154:155], v[132:135], off
	s_nop 1
	v_pk_mul_f32 v[132:133], v[136:137], v[136:137]
	v_pk_mul_f32 v[134:135], v[140:141], v[140:141]
	v_pk_mul_f32 v[136:137], v[138:139], v[138:139]
	v_add_f32_e32 v134, v134, v135
	v_add_f32_e32 v132, v132, v133
	v_pk_mul_f32 v[138:139], v[142:143], v[142:143]
	v_add_f32_e32 v132, v132, v134
	v_add_f32_e32 v133, v136, v137
	v_add_f32_e32 v132, v133, v132
	v_add_f32_e32 v133, v138, v139
	v_add_f32_e32 v132, v133, v132
	v_mov_b32_e32 v133, v132
	s_nop 1
	v_permlane16_swap_b32_e32 v133, v132
	s_waitcnt lgkmcnt(0)
	v_add_f32_e32 v132, v132, v133
	v_mov_b32_e32 v133, v132
	s_nop 1
	v_permlane32_swap_b32_e32 v133, v132
	s_and_saveexec_b64 s[72:73], s[6:7]
	s_cbranch_execz .LBB0_533
	s_waitcnt lgkmcnt(0)
	v_add_f32_e32 v134, v132, v133
	s_lshl_b32 s74, s19, 2
	v_lshlrev_b64 v[132:133], 8, v[152:153]
	s_ashr_i32 s75, s74, 31
	v_lshl_add_u64 v[132:133], s[26:27], 0, v[132:133]
	v_lshl_add_u64 v[132:133], s[74:75], 2, v[132:133]
	s_lshl_b32 s50, s37, 2
	v_lshl_add_u64 v[132:133], v[132:133], 0, s[50:51]
	global_store_dword v[132:133], v134, off
.LBB0_533:
	s_or_b64 exec, exec, s[72:73]
	v_mul_f32_e32 v137, 0xbfb8aa3b, v64
	v_exp_f32_e32 v137, v137
	v_mul_f32_e32 v136, 0xbfb8aa3b, v68
	v_exp_f32_e32 v136, v136
	v_lshlrev_b32_e32 v132, 16, v128
	v_add_f32_e32 v137, 1.0, v137
	v_rcp_f32_e32 v138, v137
	v_mul_f32_e32 v137, 0xbfb8aa3b, v69
	v_exp_f32_e32 v137, v137
	v_add_f32_e32 v136, 1.0, v136
	v_rcp_f32_e32 v136, v136
	s_waitcnt lgkmcnt(0)
	v_and_b32_e32 v133, 0xffff0000, v128
	v_add_f32_e32 v137, 1.0, v137
	v_rcp_f32_e32 v137, v137
	v_lshlrev_b32_e32 v134, 16, v130
	v_and_b32_e32 v135, 0xffff0000, v130
	v_lshlrev_b32_e32 v128, 16, v129
	v_pk_fma_f32 v[132:133], v[136:137], v[84:85], v[132:133]
	v_mul_f32_e32 v136, 0xbfb8aa3b, v65
	v_exp_f32_e32 v136, v136
	v_mul_f32_e32 v137, 0xbfb8aa3b, v66
	v_exp_f32_e32 v137, v137
	v_and_b32_e32 v129, 0xffff0000, v129
	v_add_f32_e32 v136, 1.0, v136
	v_rcp_f32_e32 v139, v136
	v_add_f32_e32 v137, 1.0, v137
	v_mul_f32_e32 v136, 0xbfb8aa3b, v70
	v_exp_f32_e32 v136, v136
	v_pk_fma_f32 v[134:135], v[138:139], v[80:81], v[134:135]
	v_rcp_f32_e32 v138, v137
	v_mul_f32_e32 v137, 0xbfb8aa3b, v71
	v_exp_f32_e32 v137, v137
	v_add_f32_e32 v136, 1.0, v136
	v_rcp_f32_e32 v136, v136
	v_lshlrev_b32_e32 v130, 16, v131
	v_add_f32_e32 v137, 1.0, v137
	v_rcp_f32_e32 v137, v137
	v_and_b32_e32 v131, 0xffff0000, v131
	v_pk_fma_f32 v[136:137], v[136:137], v[86:87], v[128:129]
	v_mul_f32_e32 v128, 0xbfb8aa3b, v67
	v_exp_f32_e32 v128, v128
	v_cvt_pk_bf16_f32 v129, v136, v137
	v_add_f32_e32 v128, 1.0, v128
	v_rcp_f32_e32 v139, v128
	v_cvt_pk_bf16_f32 v128, v132, v133
	v_pk_fma_f32 v[138:139], v[138:139], v[82:83], v[130:131]
	v_cvt_pk_bf16_f32 v130, v134, v135
	v_cvt_pk_bf16_f32 v131, v138, v139
	global_store_dwordx4 v[150:151], v[128:131], off
	s_nop 1
	v_pk_mul_f32 v[128:129], v[132:133], v[132:133]
	v_pk_mul_f32 v[130:131], v[136:137], v[136:137]
	v_pk_mul_f32 v[132:133], v[134:135], v[134:135]
	v_add_f32_e32 v130, v130, v131
	v_add_f32_e32 v128, v128, v129
	v_pk_mul_f32 v[134:135], v[138:139], v[138:139]
	v_add_f32_e32 v128, v128, v130
	v_add_f32_e32 v129, v132, v133
	v_add_f32_e32 v128, v129, v128
	v_add_f32_e32 v129, v134, v135
	v_add_f32_e32 v128, v129, v128
	v_mov_b32_e32 v129, v128
	s_nop 1
	v_permlane16_swap_b32_e32 v129, v128
	s_waitcnt lgkmcnt(0)
	v_add_f32_e32 v128, v128, v129
	v_mov_b32_e32 v129, v128
	s_nop 1
	v_permlane32_swap_b32_e32 v129, v128
	s_and_saveexec_b64 s[72:73], s[6:7]
	s_cbranch_execz .LBB0_535
	s_waitcnt lgkmcnt(0)
	v_add_f32_e32 v130, v128, v129
	s_lshl_b32 s74, s19, 2
	v_lshlrev_b64 v[128:129], 8, v[148:149]
	s_ashr_i32 s75, s74, 31
	v_lshl_add_u64 v[128:129], s[26:27], 0, v[128:129]
	v_lshl_add_u64 v[128:129], s[74:75], 2, v[128:129]
	s_lshl_b32 s50, s37, 2
	v_lshl_add_u64 v[128:129], v[128:129], 0, s[50:51]
	global_store_dword v[128:129], v130, off
.LBB0_535:
	s_or_b64 exec, exec, s[72:73]
	v_add_u32_e32 v156, 0x80, v146
	v_ashrrev_i32_e32 v157, 31, v156
	s_waitcnt lgkmcnt(0)
	v_lshlrev_b64 v[128:129], 12, v[156:157]
	v_lshl_add_u64 v[158:159], v[144:145], 0, v[128:129]
	global_load_dwordx4 v[140:143], v[158:159], off
	v_add_u32_e32 v152, 0x90, v146
	v_ashrrev_i32_e32 v153, 31, v152
	v_add_u32_e32 v148, 0xa0, v146
	v_lshlrev_b64 v[128:129], 12, v[152:153]
	v_ashrrev_i32_e32 v149, 31, v148
	v_add_u32_e32 v146, 0xb0, v146
	v_lshl_add_u64 v[154:155], v[144:145], 0, v[128:129]
	v_lshlrev_b64 v[128:129], 12, v[148:149]
	v_ashrrev_i32_e32 v147, 31, v146
	v_lshl_add_u64 v[150:151], v[144:145], 0, v[128:129]
	v_lshlrev_b64 v[128:129], 12, v[146:147]
	v_lshl_add_u64 v[144:145], v[144:145], 0, v[128:129]
	global_load_dwordx4 v[136:139], v[154:155], off
	global_load_dwordx4 v[132:135], v[150:151], off
	global_load_dwordx4 v[128:131], v[144:145], off
	v_mul_f32_e32 v161, 0xbfb8aa3b, v40
	v_exp_f32_e32 v161, v161
	v_mul_f32_e32 v160, 0xbfb8aa3b, v44
	v_exp_f32_e32 v160, v160
	v_add_f32_e32 v161, 1.0, v161
	v_rcp_f32_e32 v162, v161
	v_mul_f32_e32 v161, 0xbfb8aa3b, v45
	v_exp_f32_e32 v161, v161
	v_add_f32_e32 v160, 1.0, v160
	v_rcp_f32_e32 v160, v160
	v_add_f32_e32 v161, 1.0, v161
	v_rcp_f32_e32 v161, v161
	s_waitcnt vmcnt(3)
	v_lshlrev_b32_e32 v164, 16, v140
	v_and_b32_e32 v165, 0xffff0000, v140
	v_mul_f32_e32 v140, 0xbfb8aa3b, v41
	v_exp_f32_e32 v140, v140
	v_pk_fma_f32 v[160:161], v[160:161], v[60:61], v[164:165]
	v_lshlrev_b32_e32 v164, 16, v142
	v_and_b32_e32 v165, 0xffff0000, v142
	v_add_f32_e32 v140, 1.0, v140
	v_rcp_f32_e32 v163, v140
	v_mul_f32_e32 v140, 0xbfb8aa3b, v46
	v_exp_f32_e32 v140, v140
	v_mul_f32_e32 v142, 0xbfb8aa3b, v47
	v_pk_fma_f32 v[162:163], v[162:163], v[56:57], v[164:165]
	v_lshlrev_b32_e32 v168, 16, v141
	v_add_f32_e32 v140, 1.0, v140
	v_rcp_f32_e32 v164, v140
	v_mul_f32_e32 v140, 0xbfb8aa3b, v42
	v_and_b32_e32 v169, 0xffff0000, v141
	v_mul_f32_e32 v141, 0xbfb8aa3b, v43
	v_exp_f32_e32 v140, v140
	v_exp_f32_e32 v142, v142
	v_exp_f32_e32 v141, v141
	v_add_f32_e32 v140, 1.0, v140
	v_add_f32_e32 v142, 1.0, v142
	v_add_f32_e32 v141, 1.0, v141
	v_rcp_f32_e32 v140, v140
	v_rcp_f32_e32 v165, v142
	v_rcp_f32_e32 v141, v141
	v_lshlrev_b32_e32 v142, 16, v143
	v_and_b32_e32 v143, 0xffff0000, v143
	v_pk_fma_f32 v[164:165], v[164:165], v[62:63], v[168:169]
	v_pk_fma_f32 v[168:169], v[140:141], v[58:59], v[142:143]
	v_cvt_pk_bf16_f32 v140, v160, v161
	v_cvt_pk_bf16_f32 v141, v164, v165
	v_cvt_pk_bf16_f32 v142, v162, v163
	v_cvt_pk_bf16_f32 v143, v168, v169
	global_store_dwordx4 v[158:159], v[140:143], off
	v_pk_mul_f32 v[158:159], v[162:163], v[162:163]
	s_nop 0
	v_pk_mul_f32 v[140:141], v[160:161], v[160:161]
	v_pk_mul_f32 v[142:143], v[164:165], v[164:165]
	v_add_f32_e32 v140, v140, v141
	v_add_f32_e32 v142, v142, v143
	v_pk_mul_f32 v[160:161], v[168:169], v[168:169]
	v_add_f32_e32 v140, v140, v142
	v_add_f32_e32 v141, v158, v159
	v_add_f32_e32 v160, v160, v161
	v_add_f32_e32 v140, v141, v140
	v_add_f32_e32 v140, v160, v140
	v_mov_b32_e32 v141, v140
	s_nop 1
	v_permlane16_swap_b32_e32 v141, v140
	s_waitcnt lgkmcnt(0)
	v_add_f32_e32 v140, v140, v141
	v_mov_b32_e32 v141, v140
	s_nop 1
	v_permlane32_swap_b32_e32 v141, v140
	s_and_saveexec_b64 s[72:73], s[6:7]
	s_cbranch_execz .LBB0_537
	s_waitcnt lgkmcnt(0)
	v_add_f32_e32 v142, v140, v141
	s_lshl_b32 s74, s19, 2
	v_lshlrev_b64 v[140:141], 8, v[156:157]
	s_ashr_i32 s75, s74, 31
	v_lshl_add_u64 v[140:141], s[26:27], 0, v[140:141]
	v_lshl_add_u64 v[140:141], s[74:75], 2, v[140:141]
	s_lshl_b32 s50, s37, 2
	v_lshl_add_u64 v[140:141], v[140:141], 0, s[50:51]
	global_store_dword v[140:141], v142, off
.LBB0_537:
	s_or_b64 exec, exec, s[72:73]
	v_mul_f32_e32 v157, 0xbfb8aa3b, v24
	v_exp_f32_e32 v157, v157
	v_mul_f32_e32 v156, 0xbfb8aa3b, v28
	v_exp_f32_e32 v156, v156
	s_waitcnt vmcnt(3)
	v_lshlrev_b32_e32 v140, 16, v136
	v_add_f32_e32 v157, 1.0, v157
	v_rcp_f32_e32 v158, v157
	v_mul_f32_e32 v157, 0xbfb8aa3b, v29
	v_exp_f32_e32 v157, v157
	v_add_f32_e32 v156, 1.0, v156
	v_rcp_f32_e32 v156, v156
	s_waitcnt lgkmcnt(0)
	v_and_b32_e32 v141, 0xffff0000, v136
	v_add_f32_e32 v157, 1.0, v157
	v_rcp_f32_e32 v157, v157
	v_lshlrev_b32_e32 v142, 16, v138
	v_and_b32_e32 v143, 0xffff0000, v138
	v_lshlrev_b32_e32 v136, 16, v137
	v_pk_fma_f32 v[140:141], v[156:157], v[52:53], v[140:141]
	v_mul_f32_e32 v156, 0xbfb8aa3b, v25
	v_exp_f32_e32 v156, v156
	v_mul_f32_e32 v157, 0xbfb8aa3b, v26
	v_exp_f32_e32 v157, v157
	v_and_b32_e32 v137, 0xffff0000, v137
	v_add_f32_e32 v156, 1.0, v156
	v_rcp_f32_e32 v159, v156
	v_add_f32_e32 v157, 1.0, v157
	v_mul_f32_e32 v156, 0xbfb8aa3b, v30
	v_exp_f32_e32 v156, v156
	v_pk_fma_f32 v[142:143], v[158:159], v[48:49], v[142:143]
	v_rcp_f32_e32 v158, v157
	v_mul_f32_e32 v157, 0xbfb8aa3b, v31
	v_exp_f32_e32 v157, v157
	v_add_f32_e32 v156, 1.0, v156
	v_rcp_f32_e32 v156, v156
	v_lshlrev_b32_e32 v138, 16, v139
	v_add_f32_e32 v157, 1.0, v157
	v_rcp_f32_e32 v157, v157
	v_and_b32_e32 v139, 0xffff0000, v139
	v_pk_fma_f32 v[156:157], v[156:157], v[54:55], v[136:137]
	v_mul_f32_e32 v136, 0xbfb8aa3b, v27
	v_exp_f32_e32 v136, v136
	v_cvt_pk_bf16_f32 v137, v156, v157
	v_add_f32_e32 v136, 1.0, v136
	v_rcp_f32_e32 v159, v136
	v_cvt_pk_bf16_f32 v136, v140, v141
	v_pk_fma_f32 v[158:159], v[158:159], v[50:51], v[138:139]
	v_cvt_pk_bf16_f32 v138, v142, v143
	v_cvt_pk_bf16_f32 v139, v158, v159
	global_store_dwordx4 v[154:155], v[136:139], off
	s_nop 1
	v_pk_mul_f32 v[136:137], v[140:141], v[140:141]
	v_pk_mul_f32 v[138:139], v[156:157], v[156:157]
	v_pk_mul_f32 v[140:141], v[142:143], v[142:143]
	v_add_f32_e32 v138, v138, v139
	v_add_f32_e32 v136, v136, v137
	v_pk_mul_f32 v[142:143], v[158:159], v[158:159]
	v_add_f32_e32 v136, v136, v138
	v_add_f32_e32 v137, v140, v141
	v_add_f32_e32 v136, v137, v136
	v_add_f32_e32 v137, v142, v143
	v_add_f32_e32 v136, v137, v136
	v_mov_b32_e32 v137, v136
	s_nop 1
	v_permlane16_swap_b32_e32 v137, v136
	s_waitcnt lgkmcnt(0)
	v_add_f32_e32 v136, v136, v137
	v_mov_b32_e32 v137, v136
	s_nop 1
	v_permlane32_swap_b32_e32 v137, v136
	s_and_saveexec_b64 s[72:73], s[6:7]
	s_cbranch_execz .LBB0_539
	s_waitcnt lgkmcnt(0)
	v_add_f32_e32 v138, v136, v137
	s_lshl_b32 s74, s19, 2
	v_lshlrev_b64 v[136:137], 8, v[152:153]
	s_ashr_i32 s75, s74, 31
	v_lshl_add_u64 v[136:137], s[26:27], 0, v[136:137]
	v_lshl_add_u64 v[136:137], s[74:75], 2, v[136:137]
	s_lshl_b32 s50, s37, 2
	v_lshl_add_u64 v[136:137], v[136:137], 0, s[50:51]
	global_store_dword v[136:137], v138, off
.LBB0_539:
	s_or_b64 exec, exec, s[72:73]
	v_mul_f32_e32 v141, 0xbfb8aa3b, v8
	v_exp_f32_e32 v141, v141
	v_mul_f32_e32 v140, 0xbfb8aa3b, v12
	v_exp_f32_e32 v140, v140
	s_waitcnt vmcnt(3)
	v_lshlrev_b32_e32 v136, 16, v132
	v_add_f32_e32 v141, 1.0, v141
	v_rcp_f32_e32 v142, v141
	v_mul_f32_e32 v141, 0xbfb8aa3b, v13
	v_exp_f32_e32 v141, v141
	v_add_f32_e32 v140, 1.0, v140
	v_rcp_f32_e32 v140, v140
	s_waitcnt lgkmcnt(0)
	v_and_b32_e32 v137, 0xffff0000, v132
	v_add_f32_e32 v141, 1.0, v141
	v_rcp_f32_e32 v141, v141
	v_lshlrev_b32_e32 v138, 16, v134
	v_and_b32_e32 v139, 0xffff0000, v134
	v_lshlrev_b32_e32 v132, 16, v133
	v_pk_fma_f32 v[136:137], v[140:141], v[36:37], v[136:137]
	v_mul_f32_e32 v140, 0xbfb8aa3b, v9
	v_exp_f32_e32 v140, v140
	v_mul_f32_e32 v141, 0xbfb8aa3b, v10
	v_exp_f32_e32 v141, v141
	v_and_b32_e32 v133, 0xffff0000, v133
	v_add_f32_e32 v140, 1.0, v140
	v_rcp_f32_e32 v143, v140
	v_add_f32_e32 v141, 1.0, v141
	v_mul_f32_e32 v140, 0xbfb8aa3b, v14
	v_exp_f32_e32 v140, v140
	v_pk_fma_f32 v[138:139], v[142:143], v[32:33], v[138:139]
	v_rcp_f32_e32 v142, v141
	v_mul_f32_e32 v141, 0xbfb8aa3b, v15
	v_exp_f32_e32 v141, v141
	v_add_f32_e32 v140, 1.0, v140
	v_rcp_f32_e32 v140, v140
	v_lshlrev_b32_e32 v134, 16, v135
	v_add_f32_e32 v141, 1.0, v141
	v_rcp_f32_e32 v141, v141
	v_and_b32_e32 v135, 0xffff0000, v135
	v_pk_fma_f32 v[140:141], v[140:141], v[38:39], v[132:133]
	v_mul_f32_e32 v132, 0xbfb8aa3b, v11
	v_exp_f32_e32 v132, v132
	v_cvt_pk_bf16_f32 v133, v140, v141
	v_add_f32_e32 v132, 1.0, v132
	v_rcp_f32_e32 v143, v132
	v_cvt_pk_bf16_f32 v132, v136, v137
	v_pk_fma_f32 v[142:143], v[142:143], v[34:35], v[134:135]
	v_cvt_pk_bf16_f32 v134, v138, v139
	v_cvt_pk_bf16_f32 v135, v142, v143
	global_store_dwordx4 v[150:151], v[132:135], off
	s_nop 1
	v_pk_mul_f32 v[132:133], v[136:137], v[136:137]
	v_pk_mul_f32 v[134:135], v[140:141], v[140:141]
	v_pk_mul_f32 v[136:137], v[138:139], v[138:139]
	v_add_f32_e32 v134, v134, v135
	v_add_f32_e32 v132, v132, v133
	v_pk_mul_f32 v[138:139], v[142:143], v[142:143]
	v_add_f32_e32 v132, v132, v134
	v_add_f32_e32 v133, v136, v137
	v_add_f32_e32 v132, v133, v132
	v_add_f32_e32 v133, v138, v139
	v_add_f32_e32 v132, v133, v132
	v_mov_b32_e32 v133, v132
	s_nop 1
	v_permlane16_swap_b32_e32 v133, v132
	s_waitcnt lgkmcnt(0)
	v_add_f32_e32 v132, v132, v133
	v_mov_b32_e32 v133, v132
	s_nop 1
	v_permlane32_swap_b32_e32 v133, v132
	s_and_saveexec_b64 s[72:73], s[6:7]
	s_cbranch_execz .LBB0_541
	s_waitcnt lgkmcnt(0)
	v_add_f32_e32 v134, v132, v133
	s_lshl_b32 s74, s19, 2
	v_lshlrev_b64 v[132:133], 8, v[148:149]
	s_ashr_i32 s75, s74, 31
	v_lshl_add_u64 v[132:133], s[26:27], 0, v[132:133]
	v_lshl_add_u64 v[132:133], s[74:75], 2, v[132:133]
	s_lshl_b32 s50, s37, 2
	v_lshl_add_u64 v[132:133], v[132:133], 0, s[50:51]
	global_store_dword v[132:133], v134, off
.LBB0_541:
	s_or_b64 exec, exec, s[72:73]
	v_mul_f32_e32 v137, 0xbfb8aa3b, v0
	v_exp_f32_e32 v137, v137
	v_mul_f32_e32 v136, 0xbfb8aa3b, v4
	v_exp_f32_e32 v136, v136
	s_waitcnt vmcnt(3)
	v_lshlrev_b32_e32 v132, 16, v128
	v_add_f32_e32 v137, 1.0, v137
	v_rcp_f32_e32 v138, v137
	v_mul_f32_e32 v137, 0xbfb8aa3b, v5
	v_exp_f32_e32 v137, v137
	v_add_f32_e32 v136, 1.0, v136
	v_rcp_f32_e32 v136, v136
	s_waitcnt lgkmcnt(0)
	v_and_b32_e32 v133, 0xffff0000, v128
	v_add_f32_e32 v137, 1.0, v137
	v_rcp_f32_e32 v137, v137
	v_lshlrev_b32_e32 v134, 16, v130
	v_and_b32_e32 v135, 0xffff0000, v130
	v_lshlrev_b32_e32 v128, 16, v129
	v_pk_fma_f32 v[132:133], v[136:137], v[20:21], v[132:133]
	v_mul_f32_e32 v136, 0xbfb8aa3b, v1
	v_exp_f32_e32 v136, v136
	v_mul_f32_e32 v137, 0xbfb8aa3b, v2
	v_exp_f32_e32 v137, v137
	v_and_b32_e32 v129, 0xffff0000, v129
	v_add_f32_e32 v136, 1.0, v136
	v_rcp_f32_e32 v139, v136
	v_add_f32_e32 v137, 1.0, v137
	v_mul_f32_e32 v136, 0xbfb8aa3b, v6
	v_exp_f32_e32 v136, v136
	v_pk_fma_f32 v[134:135], v[138:139], v[16:17], v[134:135]
	v_rcp_f32_e32 v138, v137
	v_mul_f32_e32 v137, 0xbfb8aa3b, v7
	v_exp_f32_e32 v137, v137
	v_add_f32_e32 v136, 1.0, v136
	v_rcp_f32_e32 v136, v136
	v_lshlrev_b32_e32 v130, 16, v131
	v_add_f32_e32 v137, 1.0, v137
	v_rcp_f32_e32 v137, v137
	v_and_b32_e32 v131, 0xffff0000, v131
	v_pk_fma_f32 v[136:137], v[136:137], v[22:23], v[128:129]
	v_mul_f32_e32 v128, 0xbfb8aa3b, v3
	v_exp_f32_e32 v128, v128
	v_cvt_pk_bf16_f32 v129, v136, v137
	v_add_f32_e32 v128, 1.0, v128
	v_rcp_f32_e32 v139, v128
	v_cvt_pk_bf16_f32 v128, v132, v133
	v_pk_fma_f32 v[138:139], v[138:139], v[18:19], v[130:131]
	v_cvt_pk_bf16_f32 v130, v134, v135
	v_cvt_pk_bf16_f32 v131, v138, v139
	global_store_dwordx4 v[144:145], v[128:131], off
	s_nop 1
	v_pk_mul_f32 v[128:129], v[132:133], v[132:133]
	v_pk_mul_f32 v[130:131], v[136:137], v[136:137]
	v_pk_mul_f32 v[132:133], v[134:135], v[134:135]
	v_add_f32_e32 v130, v130, v131
	v_add_f32_e32 v128, v128, v129
	v_pk_mul_f32 v[134:135], v[138:139], v[138:139]
	v_add_f32_e32 v128, v128, v130
	v_add_f32_e32 v129, v132, v133
	v_add_f32_e32 v128, v129, v128
	v_add_f32_e32 v129, v134, v135
	v_add_f32_e32 v128, v129, v128
	v_mov_b32_e32 v129, v128
	s_nop 1
	v_permlane16_swap_b32_e32 v129, v128
	s_waitcnt lgkmcnt(0)
	v_add_f32_e32 v128, v128, v129
	v_mov_b32_e32 v129, v128
	s_nop 1
	v_permlane32_swap_b32_e32 v129, v128
	s_and_saveexec_b64 s[72:73], s[6:7]
	s_cbranch_execz .LBB0_543
	s_waitcnt lgkmcnt(0)
	v_add_f32_e32 v130, v128, v129
	s_lshl_b32 s74, s19, 2
	v_lshlrev_b64 v[128:129], 8, v[146:147]
	s_ashr_i32 s75, s74, 31
	v_lshl_add_u64 v[128:129], s[26:27], 0, v[128:129]
	v_lshl_add_u64 v[128:129], s[74:75], 2, v[128:129]
	s_lshl_b32 s50, s37, 2
	v_lshl_add_u64 v[128:129], v[128:129], 0, s[50:51]
	global_store_dword v[128:129], v130, off

.LBB0_544:
	s_and_b64 vcc, exec, s[72:73]
	s_cbranch_vccz .LBB0_578
	v_add_u32_e32 v158, s78, v202
	v_lshl_or_b32 v128, s19, 8, v238
	s_waitcnt lgkmcnt(0)
	v_ashrrev_i32_e32 v129, 31, v128
	v_ashrrev_i32_e32 v159, 31, v158
	v_lshl_add_u64 v[156:157], v[128:129], 1, s[24:25]
	v_lshlrev_b64 v[128:129], 12, v[158:159]
	v_lshl_add_u64 v[172:173], v[156:157], 0, v[128:129]
	global_load_dwordx4 v[178:181], v[172:173], off
	global_load_dwordx4 v[152:155], v[172:173], off offset:256
	v_or_b32_e32 v170, 16, v158
	v_or_b32_e32 v166, 32, v158
	v_or_b32_e32 v162, 48, v158
	v_ashrrev_i32_e32 v171, 31, v170
	v_ashrrev_i32_e32 v167, 31, v166
	v_ashrrev_i32_e32 v163, 31, v162
	v_lshlrev_b64 v[128:129], 12, v[170:171]
	v_lshlrev_b64 v[130:131], 12, v[166:167]
	v_lshlrev_b64 v[132:133], 12, v[162:163]
	v_lshl_add_u64 v[168:169], v[156:157], 0, v[128:129]
	v_lshl_add_u64 v[164:165], v[156:157], 0, v[130:131]
	v_lshl_add_u64 v[160:161], v[156:157], 0, v[132:133]
	global_load_dwordx4 v[148:151], v[168:169], off
	global_load_dwordx4 v[144:147], v[168:169], off offset:256
	global_load_dwordx4 v[140:143], v[164:165], off
	global_load_dwordx4 v[136:139], v[164:165], off offset:256
	global_load_dwordx4 v[132:135], v[160:161], off
	global_load_dwordx4 v[128:131], v[160:161], off offset:256
	v_and_b32_e32 v175, 64, v231
	v_xor_b32_e32 v174, 16, v231
	v_add_u32_e32 v175, 64, v175
	v_xor_b32_e32 v176, 32, v231
	v_cmp_lt_i32_e32 vcc, v174, v175
	s_waitcnt vmcnt(0)
	v_lshlrev_b32_e32 v182, 16, v180
	v_cndmask_b32_e32 v174, v231, v174, vcc
	v_cmp_lt_i32_e32 vcc, v176, v175
	v_and_b32_e32 v175, 0xffff0000, v178
	v_and_b32_e32 v183, 0xffff0000, v180
	v_cndmask_b32_e32 v177, v231, v176, vcc
	v_lshlrev_b32_e32 v176, 2, v174
	v_lshlrev_b32_e32 v174, 16, v178
	v_lshlrev_b32_e32 v178, 16, v179
	v_and_b32_e32 v179, 0xffff0000, v179
	v_pk_add_f32 v[184:185], v[126:127], v[178:179]
	v_pk_add_f32 v[178:179], v[124:125], v[174:175]
	v_lshlrev_b32_e32 v180, 16, v181
	v_and_b32_e32 v181, 0xffff0000, v181
	v_pk_add_f32 v[182:183], v[120:121], v[182:183]
	v_mul_f32_e32 v174, v179, v179
	v_mul_f32_e32 v175, v185, v185
	v_pk_add_f32 v[186:187], v[122:123], v[180:181]
	v_mul_f32_e32 v180, v183, v183
	v_fmac_f32_e32 v174, v178, v178
	v_fmac_f32_e32 v175, v184, v184
	v_mul_f32_e32 v181, v187, v187
	v_fmac_f32_e32 v180, v182, v182
	v_add_f32_e32 v174, v174, v175
	v_add_f32_e32 v174, v180, v174
	v_fmac_f32_e32 v181, v186, v186
	v_add_f32_e32 v181, v181, v174
	v_mov_b32_e32 v188, v181
	s_nop 1
	v_permlane16_swap_b32_e32 v188, v181
	v_lshlrev_b32_e32 v177, 2, v177
	v_lshlrev_b64 v[174:175], 8, v[158:159]
	v_cvt_pk_bf16_f32 v180, v178, v179
	v_lshl_add_u64 v[174:175], s[26:27], 0, v[174:175]
	s_waitcnt lgkmcnt(0)
	v_add_f32_e32 v159, v181, v188
	v_mov_b32_e32 v178, v159
	s_nop 1
	v_permlane32_swap_b32_e32 v178, v159
	v_cvt_pk_bf16_f32 v181, v184, v185
	v_cvt_pk_bf16_f32 v182, v182, v183
	v_cvt_pk_bf16_f32 v183, v186, v187
	global_store_dwordx4 v[172:173], v[180:183], off
	s_and_saveexec_b64 s[72:73], s[6:7]
	s_cbranch_execz .LBB0_547
	s_lshl_b32 s74, s19, 3
	s_ashr_i32 s75, s74, 31
	s_waitcnt lgkmcnt(0)
	v_add_f32_e32 v159, v159, v178
	v_lshl_add_u64 v[178:179], s[74:75], 2, v[174:175]
	s_lshl_b32 s50, s37, 2
	v_lshl_add_u64 v[178:179], v[178:179], 0, s[50:51]
	global_store_dword v[178:179], v159, off
.LBB0_547:
	s_or_b64 exec, exec, s[72:73]
	s_waitcnt lgkmcnt(0)
	v_lshlrev_b32_e32 v178, 16, v152
	v_and_b32_e32 v179, 0xffff0000, v152
	v_lshlrev_b32_e32 v152, 16, v153
	v_and_b32_e32 v153, 0xffff0000, v153
	v_pk_add_f32 v[182:183], v[110:111], v[152:153]
	v_pk_add_f32 v[152:153], v[108:109], v[178:179]
	v_lshlrev_b32_e32 v180, 16, v154
	v_and_b32_e32 v181, 0xffff0000, v154
	v_mul_f32_e32 v159, v153, v153
	v_mul_f32_e32 v178, v183, v183
	v_pk_add_f32 v[180:181], v[104:105], v[180:181]
	v_fmac_f32_e32 v159, v152, v152
	v_fmac_f32_e32 v178, v182, v182
	v_lshlrev_b32_e32 v154, 16, v155
	v_and_b32_e32 v155, 0xffff0000, v155
	v_add_f32_e32 v159, v159, v178
	v_mul_f32_e32 v178, v181, v181
	v_pk_add_f32 v[154:155], v[106:107], v[154:155]
	v_fmac_f32_e32 v178, v180, v180
	v_add_f32_e32 v159, v178, v159
	v_mul_f32_e32 v178, v155, v155
	v_fmac_f32_e32 v178, v154, v154
	v_add_f32_e32 v159, v178, v159
	v_mov_b32_e32 v179, v159
	s_nop 1
	v_permlane16_swap_b32_e32 v179, v159
	v_cvt_pk_bf16_f32 v178, v152, v153
	v_cvt_pk_bf16_f32 v180, v180, v181
	v_cvt_pk_bf16_f32 v181, v154, v155
	s_waitcnt lgkmcnt(0)
	v_add_f32_e32 v152, v159, v179
	v_mov_b32_e32 v153, v152
	s_nop 1
	v_permlane32_swap_b32_e32 v153, v152
	v_cvt_pk_bf16_f32 v179, v182, v183
	global_store_dwordx4 v[172:173], v[178:181], off offset:256
	s_and_saveexec_b64 s[72:73], s[6:7]
	s_cbranch_execz .LBB0_549
	s_lshl_b32 s74, s19, 3
	s_ashr_i32 s75, s74, 31
	s_waitcnt lgkmcnt(0)
	v_add_f32_e32 v154, v152, v153
	v_lshl_add_u64 v[152:153], s[74:75], 2, v[174:175]
	s_lshl_b32 s50, s37, 2
	v_lshl_add_u64 v[152:153], v[152:153], 0, s[50:51]
	global_store_dword v[152:153], v154, off offset:16
.LBB0_549:
	s_or_b64 exec, exec, s[72:73]
	v_lshlrev_b32_e32 v152, 16, v148
	s_waitcnt lgkmcnt(0)
	v_and_b32_e32 v153, 0xffff0000, v148
	v_lshlrev_b32_e32 v148, 16, v149
	v_and_b32_e32 v149, 0xffff0000, v149
	v_pk_add_f32 v[172:173], v[118:119], v[148:149]
	v_pk_add_f32 v[152:153], v[116:117], v[152:153]
	v_lshlrev_b32_e32 v154, 16, v150
	v_and_b32_e32 v155, 0xffff0000, v150
	v_mul_f32_e32 v148, v153, v153
	v_mul_f32_e32 v149, v173, v173
	v_pk_add_f32 v[154:155], v[112:113], v[154:155]
	v_fmac_f32_e32 v148, v152, v152
	v_fmac_f32_e32 v149, v172, v172
	v_lshlrev_b32_e32 v150, 16, v151
	v_and_b32_e32 v151, 0xffff0000, v151
	v_add_f32_e32 v148, v148, v149
	v_mul_f32_e32 v149, v155, v155
	v_pk_add_f32 v[174:175], v[114:115], v[150:151]
	v_fmac_f32_e32 v149, v154, v154
	v_add_f32_e32 v148, v149, v148
	v_mul_f32_e32 v149, v175, v175
	v_fmac_f32_e32 v149, v174, v174
	v_add_f32_e32 v150, v149, v148
	v_mov_b32_e32 v151, v150
	s_nop 1
	v_permlane16_swap_b32_e32 v151, v150
	v_lshlrev_b64 v[148:149], 8, v[170:171]
	v_lshl_add_u64 v[148:149], s[26:27], 0, v[148:149]
	v_cvt_pk_bf16_f32 v152, v152, v153
	v_cvt_pk_bf16_f32 v153, v172, v173
	s_waitcnt lgkmcnt(0)
	v_add_f32_e32 v150, v150, v151
	v_mov_b32_e32 v151, v150
	s_nop 1
	v_permlane32_swap_b32_e32 v151, v150
	v_cvt_pk_bf16_f32 v154, v154, v155
	v_cvt_pk_bf16_f32 v155, v174, v175
	global_store_dwordx4 v[168:169], v[152:155], off
	s_and_saveexec_b64 s[72:73], s[6:7]
	s_cbranch_execz .LBB0_551
	s_lshl_b32 s74, s19, 3
	s_ashr_i32 s75, s74, 31
	s_waitcnt lgkmcnt(0)
	v_add_f32_e32 v152, v150, v151
	v_lshl_add_u64 v[150:151], s[74:75], 2, v[148:149]
	s_lshl_b32 s50, s37, 2
	v_lshl_add_u64 v[150:151], v[150:151], 0, s[50:51]
	global_store_dword v[150:151], v152, off
.LBB0_551:
	s_or_b64 exec, exec, s[72:73]
	v_lshlrev_b32_e32 v150, 16, v144
	s_waitcnt lgkmcnt(0)
	v_and_b32_e32 v151, 0xffff0000, v144
	v_lshlrev_b32_e32 v144, 16, v145
	v_and_b32_e32 v145, 0xffff0000, v145
	v_pk_add_f32 v[154:155], v[94:95], v[144:145]
	v_pk_add_f32 v[144:145], v[92:93], v[150:151]
	v_lshlrev_b32_e32 v152, 16, v146
	v_and_b32_e32 v153, 0xffff0000, v146
	v_mul_f32_e32 v150, v145, v145
	v_mul_f32_e32 v151, v155, v155
	v_pk_add_f32 v[152:153], v[88:89], v[152:153]
	v_fmac_f32_e32 v150, v144, v144
	v_fmac_f32_e32 v151, v154, v154
	v_lshlrev_b32_e32 v146, 16, v147
	v_and_b32_e32 v147, 0xffff0000, v147
	v_add_f32_e32 v150, v150, v151
	v_mul_f32_e32 v151, v153, v153
	v_pk_add_f32 v[146:147], v[90:91], v[146:147]
	v_fmac_f32_e32 v151, v152, v152
	v_add_f32_e32 v150, v151, v150
	v_mul_f32_e32 v151, v147, v147
	v_fmac_f32_e32 v151, v146, v146
	v_add_f32_e32 v151, v151, v150
	v_mov_b32_e32 v159, v151
	s_nop 1
	v_permlane16_swap_b32_e32 v159, v151
	v_cvt_pk_bf16_f32 v150, v144, v145
	v_cvt_pk_bf16_f32 v152, v152, v153
	v_cvt_pk_bf16_f32 v153, v146, v147
	s_waitcnt lgkmcnt(0)
	v_add_f32_e32 v144, v151, v159
	v_mov_b32_e32 v145, v144
	s_nop 1
	v_permlane32_swap_b32_e32 v145, v144
	v_cvt_pk_bf16_f32 v151, v154, v155
	global_store_dwordx4 v[168:169], v[150:153], off offset:256
	s_and_saveexec_b64 s[72:73], s[6:7]
	s_cbranch_execz .LBB0_553
	s_lshl_b32 s74, s19, 3
	s_ashr_i32 s75, s74, 31
	s_waitcnt lgkmcnt(0)
	v_add_f32_e32 v146, v144, v145
	v_lshl_add_u64 v[144:145], s[74:75], 2, v[148:149]
	s_lshl_b32 s50, s37, 2
	v_lshl_add_u64 v[144:145], v[144:145], 0, s[50:51]
	global_store_dword v[144:145], v146, off offset:16
.LBB0_553:
	s_or_b64 exec, exec, s[72:73]
	v_lshlrev_b32_e32 v144, 16, v140
	s_waitcnt lgkmcnt(0)
	v_and_b32_e32 v145, 0xffff0000, v140
	v_lshlrev_b32_e32 v140, 16, v141
	v_and_b32_e32 v141, 0xffff0000, v141
	v_pk_add_f32 v[148:149], v[102:103], v[140:141]
	v_pk_add_f32 v[144:145], v[100:101], v[144:145]
	v_lshlrev_b32_e32 v146, 16, v142
	v_and_b32_e32 v147, 0xffff0000, v142
	v_mul_f32_e32 v140, v145, v145
	v_mul_f32_e32 v141, v149, v149
	v_pk_add_f32 v[146:147], v[96:97], v[146:147]
	v_fmac_f32_e32 v140, v144, v144
	v_fmac_f32_e32 v141, v148, v148
	v_lshlrev_b32_e32 v142, 16, v143
	v_and_b32_e32 v143, 0xffff0000, v143
	v_add_f32_e32 v140, v140, v141
	v_mul_f32_e32 v141, v147, v147
	v_pk_add_f32 v[150:151], v[98:99], v[142:143]
	v_fmac_f32_e32 v141, v146, v146
	v_add_f32_e32 v140, v141, v140
	v_mul_f32_e32 v141, v151, v151
	v_fmac_f32_e32 v141, v150, v150
	v_add_f32_e32 v142, v141, v140
	v_mov_b32_e32 v143, v142
	s_nop 1
	v_permlane16_swap_b32_e32 v143, v142
	v_lshlrev_b64 v[140:141], 8, v[166:167]
	v_lshl_add_u64 v[140:141], s[26:27], 0, v[140:141]
	v_cvt_pk_bf16_f32 v144, v144, v145
	v_cvt_pk_bf16_f32 v145, v148, v149
	s_waitcnt lgkmcnt(0)
	v_add_f32_e32 v142, v142, v143
	v_mov_b32_e32 v143, v142
	s_nop 1
	v_permlane32_swap_b32_e32 v143, v142
	v_cvt_pk_bf16_f32 v146, v146, v147
	v_cvt_pk_bf16_f32 v147, v150, v151
	global_store_dwordx4 v[164:165], v[144:147], off
	s_and_saveexec_b64 s[72:73], s[6:7]
	s_cbranch_execz .LBB0_555
	s_lshl_b32 s74, s19, 3
	s_ashr_i32 s75, s74, 31
	s_waitcnt lgkmcnt(0)
	v_add_f32_e32 v144, v142, v143
	v_lshl_add_u64 v[142:143], s[74:75], 2, v[140:141]
	s_lshl_b32 s50, s37, 2
	v_lshl_add_u64 v[142:143], v[142:143], 0, s[50:51]
	global_store_dword v[142:143], v144, off
.LBB0_555:
	s_or_b64 exec, exec, s[72:73]
	v_lshlrev_b32_e32 v142, 16, v136
	s_waitcnt lgkmcnt(0)
	v_and_b32_e32 v143, 0xffff0000, v136
	v_lshlrev_b32_e32 v136, 16, v137
	v_and_b32_e32 v137, 0xffff0000, v137
	v_pk_add_f32 v[146:147], v[78:79], v[136:137]
	v_pk_add_f32 v[136:137], v[76:77], v[142:143]
	v_lshlrev_b32_e32 v144, 16, v138
	v_and_b32_e32 v145, 0xffff0000, v138
	v_mul_f32_e32 v142, v137, v137
	v_mul_f32_e32 v143, v147, v147
	v_pk_add_f32 v[144:145], v[72:73], v[144:145]
	v_fmac_f32_e32 v142, v136, v136
	v_fmac_f32_e32 v143, v146, v146
	v_lshlrev_b32_e32 v138, 16, v139
	v_and_b32_e32 v139, 0xffff0000, v139
	v_add_f32_e32 v142, v142, v143
	v_mul_f32_e32 v143, v145, v145
	v_pk_add_f32 v[138:139], v[74:75], v[138:139]
	v_fmac_f32_e32 v143, v144, v144
	v_add_f32_e32 v142, v143, v142
	v_mul_f32_e32 v143, v139, v139
	v_fmac_f32_e32 v143, v138, v138
	v_add_f32_e32 v143, v143, v142
	v_mov_b32_e32 v148, v143
	s_nop 1
	v_permlane16_swap_b32_e32 v148, v143
	v_cvt_pk_bf16_f32 v142, v136, v137
	v_cvt_pk_bf16_f32 v144, v144, v145
	v_cvt_pk_bf16_f32 v145, v138, v139
	s_waitcnt lgkmcnt(0)
	v_add_f32_e32 v136, v143, v148
	v_mov_b32_e32 v137, v136
	s_nop 1
	v_permlane32_swap_b32_e32 v137, v136
	v_cvt_pk_bf16_f32 v143, v146, v147
	global_store_dwordx4 v[164:165], v[142:145], off offset:256
	s_and_saveexec_b64 s[72:73], s[6:7]
	s_cbranch_execz .LBB0_557
	s_lshl_b32 s74, s19, 3
	s_ashr_i32 s75, s74, 31
	s_waitcnt lgkmcnt(0)
	v_add_f32_e32 v138, v136, v137
	v_lshl_add_u64 v[136:137], s[74:75], 2, v[140:141]
	s_lshl_b32 s50, s37, 2
	v_lshl_add_u64 v[136:137], v[136:137], 0, s[50:51]
	global_store_dword v[136:137], v138, off offset:16
.LBB0_557:
	s_or_b64 exec, exec, s[72:73]
	v_lshlrev_b32_e32 v136, 16, v132
	s_waitcnt lgkmcnt(0)
	v_and_b32_e32 v137, 0xffff0000, v132
	v_lshlrev_b32_e32 v132, 16, v133
	v_and_b32_e32 v133, 0xffff0000, v133
	v_pk_add_f32 v[140:141], v[86:87], v[132:133]
	v_pk_add_f32 v[136:137], v[84:85], v[136:137]
	v_lshlrev_b32_e32 v138, 16, v134
	v_and_b32_e32 v139, 0xffff0000, v134
	v_mul_f32_e32 v132, v137, v137
	v_mul_f32_e32 v133, v141, v141
	v_pk_add_f32 v[138:139], v[80:81], v[138:139]
	v_fmac_f32_e32 v132, v136, v136
	v_fmac_f32_e32 v133, v140, v140
	v_lshlrev_b32_e32 v134, 16, v135
	v_and_b32_e32 v135, 0xffff0000, v135
	v_add_f32_e32 v132, v132, v133
	v_mul_f32_e32 v133, v139, v139
	v_pk_add_f32 v[142:143], v[82:83], v[134:135]
	v_fmac_f32_e32 v133, v138, v138
	v_add_f32_e32 v132, v133, v132
	v_mul_f32_e32 v133, v143, v143
	v_fmac_f32_e32 v133, v142, v142
	v_add_f32_e32 v134, v133, v132
	v_mov_b32_e32 v135, v134
	s_nop 1
	v_permlane16_swap_b32_e32 v135, v134
	v_lshlrev_b64 v[132:133], 8, v[162:163]
	v_lshl_add_u64 v[132:133], s[26:27], 0, v[132:133]
	v_cvt_pk_bf16_f32 v136, v136, v137
	v_cvt_pk_bf16_f32 v137, v140, v141
	s_waitcnt lgkmcnt(0)
	v_add_f32_e32 v134, v134, v135
	v_mov_b32_e32 v135, v134
	s_nop 1
	v_permlane32_swap_b32_e32 v135, v134
	v_cvt_pk_bf16_f32 v138, v138, v139
	v_cvt_pk_bf16_f32 v139, v142, v143
	global_store_dwordx4 v[160:161], v[136:139], off
	s_and_saveexec_b64 s[72:73], s[6:7]
	s_cbranch_execz .LBB0_559
	s_lshl_b32 s74, s19, 3
	s_ashr_i32 s75, s74, 31
	s_waitcnt lgkmcnt(0)
	v_add_f32_e32 v136, v134, v135
	v_lshl_add_u64 v[134:135], s[74:75], 2, v[132:133]
	s_lshl_b32 s50, s37, 2
	v_lshl_add_u64 v[134:135], v[134:135], 0, s[50:51]
	global_store_dword v[134:135], v136, off
.LBB0_559:
	s_or_b64 exec, exec, s[72:73]
	v_lshlrev_b32_e32 v134, 16, v128
	s_waitcnt lgkmcnt(0)
	v_and_b32_e32 v135, 0xffff0000, v128
	v_lshlrev_b32_e32 v128, 16, v129
	v_and_b32_e32 v129, 0xffff0000, v129
	v_pk_add_f32 v[138:139], v[70:71], v[128:129]
	v_pk_add_f32 v[128:129], v[68:69], v[134:135]
	v_lshlrev_b32_e32 v136, 16, v130
	v_and_b32_e32 v137, 0xffff0000, v130
	v_mul_f32_e32 v134, v129, v129
	v_mul_f32_e32 v135, v139, v139
	v_pk_add_f32 v[136:137], v[64:65], v[136:137]
	v_fmac_f32_e32 v134, v128, v128
	v_fmac_f32_e32 v135, v138, v138
	v_lshlrev_b32_e32 v130, 16, v131
	v_and_b32_e32 v131, 0xffff0000, v131
	v_add_f32_e32 v134, v134, v135
	v_mul_f32_e32 v135, v137, v137
	v_pk_add_f32 v[130:131], v[66:67], v[130:131]
	v_fmac_f32_e32 v135, v136, v136
	v_add_f32_e32 v134, v135, v134
	v_mul_f32_e32 v135, v131, v131
	v_fmac_f32_e32 v135, v130, v130
	v_add_f32_e32 v135, v135, v134
	v_mov_b32_e32 v140, v135
	s_nop 1
	v_permlane16_swap_b32_e32 v140, v135
	v_cvt_pk_bf16_f32 v134, v128, v129
	v_cvt_pk_bf16_f32 v136, v136, v137
	v_cvt_pk_bf16_f32 v137, v130, v131
	s_waitcnt lgkmcnt(0)
	v_add_f32_e32 v128, v135, v140
	v_mov_b32_e32 v129, v128
	s_nop 1
	v_permlane32_swap_b32_e32 v129, v128
	v_cvt_pk_bf16_f32 v135, v138, v139
	global_store_dwordx4 v[160:161], v[134:137], off offset:256
	s_and_saveexec_b64 s[72:73], s[6:7]
	s_cbranch_execz .LBB0_561
	s_lshl_b32 s74, s19, 3
	s_ashr_i32 s75, s74, 31
	s_waitcnt lgkmcnt(0)
	v_add_f32_e32 v130, v128, v129
	v_lshl_add_u64 v[128:129], s[74:75], 2, v[132:133]
	s_lshl_b32 s50, s37, 2
	v_lshl_add_u64 v[128:129], v[128:129], 0, s[50:51]
	global_store_dword v[128:129], v130, off offset:16
.LBB0_561:
	s_or_b64 exec, exec, s[72:73]
	v_add_u32_e32 v170, 0x80, v158
	v_ashrrev_i32_e32 v171, 31, v170
	s_waitcnt lgkmcnt(0)
	v_lshlrev_b64 v[128:129], 12, v[170:171]
	v_lshl_add_u64 v[168:169], v[156:157], 0, v[128:129]
	global_load_dwordx4 v[128:131], v[168:169], off
	global_load_dwordx4 v[152:155], v[168:169], off offset:256
	v_add_u32_e32 v166, 0x90, v158
	v_ashrrev_i32_e32 v167, 31, v166
	v_add_u32_e32 v162, 0xa0, v158
	v_ashrrev_i32_e32 v163, 31, v162
	v_add_u32_e32 v158, 0xb0, v158
	v_ashrrev_i32_e32 v159, 31, v158
	v_lshlrev_b64 v[170:171], 8, v[170:171]
	v_lshl_add_u64 v[170:171], s[26:27], 0, v[170:171]
	s_waitcnt vmcnt(1)
	v_lshlrev_b32_e32 v172, 16, v128
	v_and_b32_e32 v173, 0xffff0000, v128
	v_lshlrev_b32_e32 v174, 16, v129
	v_and_b32_e32 v175, 0xffff0000, v129
	v_lshlrev_b64 v[128:129], 12, v[166:167]
	v_lshl_add_u64 v[164:165], v[156:157], 0, v[128:129]
	v_lshlrev_b64 v[128:129], 12, v[162:163]
	v_lshl_add_u64 v[160:161], v[156:157], 0, v[128:129]
	v_lshlrev_b64 v[128:129], 12, v[158:159]
	v_lshl_add_u64 v[156:157], v[156:157], 0, v[128:129]
	v_lshlrev_b32_e32 v178, 16, v130
	v_and_b32_e32 v179, 0xffff0000, v130
	v_lshlrev_b32_e32 v180, 16, v131
	v_and_b32_e32 v181, 0xffff0000, v131
	global_load_dwordx4 v[148:151], v[164:165], off
	global_load_dwordx4 v[144:147], v[164:165], off offset:256
	global_load_dwordx4 v[140:143], v[160:161], off
	global_load_dwordx4 v[136:139], v[160:161], off offset:256
	global_load_dwordx4 v[132:135], v[156:157], off
	global_load_dwordx4 v[128:131], v[156:157], off offset:256
	v_pk_add_f32 v[182:183], v[62:63], v[174:175]
	v_pk_add_f32 v[184:185], v[60:61], v[172:173]
	v_pk_add_f32 v[180:181], v[58:59], v[180:181]
	v_pk_add_f32 v[178:179], v[56:57], v[178:179]
	v_cvt_pk_bf16_f32 v172, v184, v185
	v_cvt_pk_bf16_f32 v173, v182, v183
	v_cvt_pk_bf16_f32 v174, v178, v179
	v_cvt_pk_bf16_f32 v175, v180, v181
	global_store_dwordx4 v[168:169], v[172:175], off
	s_nop 1
	v_mul_f32_e32 v172, v185, v185
	v_mul_f32_e32 v173, v183, v183
	v_fmac_f32_e32 v172, v184, v184
	v_fmac_f32_e32 v173, v182, v182
	v_add_f32_e32 v172, v172, v173
	v_mul_f32_e32 v173, v179, v179
	v_fmac_f32_e32 v173, v178, v178
	v_add_f32_e32 v172, v173, v172
	v_mul_f32_e32 v173, v181, v181
	v_fmac_f32_e32 v173, v180, v180
	v_add_f32_e32 v172, v173, v172
	v_mov_b32_e32 v173, v172
	s_nop 1
	v_permlane16_swap_b32_e32 v173, v172
	s_waitcnt lgkmcnt(0)
	v_add_f32_e32 v172, v172, v173
	v_mov_b32_e32 v173, v172
	s_nop 1
	v_permlane32_swap_b32_e32 v173, v172
	s_and_saveexec_b64 s[72:73], s[6:7]
	s_cbranch_execz .LBB0_563
	s_lshl_b32 s74, s19, 3
	s_ashr_i32 s75, s74, 31
	s_waitcnt lgkmcnt(0)
	v_add_f32_e32 v174, v172, v173
	v_lshl_add_u64 v[172:173], s[74:75], 2, v[170:171]
	s_lshl_b32 s50, s37, 2
	v_lshl_add_u64 v[172:173], v[172:173], 0, s[50:51]
	global_store_dword v[172:173], v174, off
.LBB0_563:
	s_or_b64 exec, exec, s[72:73]
	s_waitcnt vmcnt(7)
	v_lshlrev_b32_e32 v172, 16, v152
	s_waitcnt lgkmcnt(0)
	v_and_b32_e32 v173, 0xffff0000, v152
	v_lshlrev_b32_e32 v152, 16, v153
	v_and_b32_e32 v153, 0xffff0000, v153
	v_pk_add_f32 v[178:179], v[46:47], v[152:153]
	v_pk_add_f32 v[152:153], v[44:45], v[172:173]
	v_lshlrev_b32_e32 v174, 16, v154
	v_and_b32_e32 v175, 0xffff0000, v154
	v_mul_f32_e32 v172, v153, v153
	v_mul_f32_e32 v173, v179, v179
	v_pk_add_f32 v[174:175], v[40:41], v[174:175]
	v_fmac_f32_e32 v172, v152, v152
	v_fmac_f32_e32 v173, v178, v178
	v_lshlrev_b32_e32 v154, 16, v155
	v_and_b32_e32 v155, 0xffff0000, v155
	v_add_f32_e32 v172, v172, v173
	v_mul_f32_e32 v173, v175, v175
	v_pk_add_f32 v[154:155], v[42:43], v[154:155]
	v_fmac_f32_e32 v173, v174, v174
	v_add_f32_e32 v172, v173, v172
	v_mul_f32_e32 v173, v155, v155
	v_fmac_f32_e32 v173, v154, v154
	v_add_f32_e32 v173, v173, v172
	v_mov_b32_e32 v180, v173
	s_nop 1
	v_permlane16_swap_b32_e32 v180, v173
	v_cvt_pk_bf16_f32 v172, v152, v153
	v_cvt_pk_bf16_f32 v174, v174, v175
	v_cvt_pk_bf16_f32 v175, v154, v155
	s_waitcnt lgkmcnt(0)
	v_add_f32_e32 v152, v173, v180
	v_mov_b32_e32 v153, v152
	s_nop 1
	v_permlane32_swap_b32_e32 v153, v152
	v_cvt_pk_bf16_f32 v173, v178, v179
	global_store_dwordx4 v[168:169], v[172:175], off offset:256
	s_and_saveexec_b64 s[72:73], s[6:7]
	s_cbranch_execz .LBB0_565
	s_lshl_b32 s74, s19, 3
	s_ashr_i32 s75, s74, 31
	s_waitcnt lgkmcnt(0)
	v_add_f32_e32 v154, v152, v153
	v_lshl_add_u64 v[152:153], s[74:75], 2, v[170:171]
	s_lshl_b32 s50, s37, 2
	v_lshl_add_u64 v[152:153], v[152:153], 0, s[50:51]
	global_store_dword v[152:153], v154, off offset:16
.LBB0_565:
	s_or_b64 exec, exec, s[72:73]
	s_waitcnt vmcnt(7)
	v_lshlrev_b32_e32 v152, 16, v148
	s_waitcnt lgkmcnt(0)
	v_and_b32_e32 v153, 0xffff0000, v148
	v_lshlrev_b32_e32 v148, 16, v149
	v_and_b32_e32 v149, 0xffff0000, v149
	v_pk_add_f32 v[168:169], v[54:55], v[148:149]
	v_pk_add_f32 v[152:153], v[52:53], v[152:153]
	v_lshlrev_b32_e32 v154, 16, v150
	v_and_b32_e32 v155, 0xffff0000, v150
	v_mul_f32_e32 v148, v153, v153
	v_mul_f32_e32 v149, v169, v169
	v_pk_add_f32 v[154:155], v[48:49], v[154:155]
	v_fmac_f32_e32 v148, v152, v152
	v_fmac_f32_e32 v149, v168, v168
	v_lshlrev_b32_e32 v150, 16, v151
	v_and_b32_e32 v151, 0xffff0000, v151
	v_add_f32_e32 v148, v148, v149
	v_mul_f32_e32 v149, v155, v155
	v_pk_add_f32 v[170:171], v[50:51], v[150:151]
	v_fmac_f32_e32 v149, v154, v154
	v_add_f32_e32 v148, v149, v148
	v_mul_f32_e32 v149, v171, v171
	v_fmac_f32_e32 v149, v170, v170
	v_add_f32_e32 v150, v149, v148
	v_mov_b32_e32 v151, v150
	s_nop 1
	v_permlane16_swap_b32_e32 v151, v150
	v_lshlrev_b64 v[148:149], 8, v[166:167]
	v_lshl_add_u64 v[148:149], s[26:27], 0, v[148:149]
	v_cvt_pk_bf16_f32 v152, v152, v153
	v_cvt_pk_bf16_f32 v153, v168, v169
	s_waitcnt lgkmcnt(0)
	v_add_f32_e32 v150, v150, v151
	v_mov_b32_e32 v151, v150
	s_nop 1
	v_permlane32_swap_b32_e32 v151, v150
	v_cvt_pk_bf16_f32 v154, v154, v155
	v_cvt_pk_bf16_f32 v155, v170, v171
	global_store_dwordx4 v[164:165], v[152:155], off
	s_and_saveexec_b64 s[72:73], s[6:7]
	s_cbranch_execz .LBB0_567
	s_lshl_b32 s74, s19, 3
	s_ashr_i32 s75, s74, 31
	s_waitcnt lgkmcnt(0)
	v_add_f32_e32 v152, v150, v151
	v_lshl_add_u64 v[150:151], s[74:75], 2, v[148:149]
	s_lshl_b32 s50, s37, 2
	v_lshl_add_u64 v[150:151], v[150:151], 0, s[50:51]
	global_store_dword v[150:151], v152, off
.LBB0_567:
	s_or_b64 exec, exec, s[72:73]
	s_waitcnt vmcnt(7)
	v_lshlrev_b32_e32 v150, 16, v144
	s_waitcnt lgkmcnt(0)
	v_and_b32_e32 v151, 0xffff0000, v144
	v_lshlrev_b32_e32 v144, 16, v145
	v_and_b32_e32 v145, 0xffff0000, v145
	v_pk_add_f32 v[154:155], v[30:31], v[144:145]
	v_pk_add_f32 v[144:145], v[28:29], v[150:151]
	v_lshlrev_b32_e32 v152, 16, v146
	v_and_b32_e32 v153, 0xffff0000, v146
	v_mul_f32_e32 v150, v145, v145
	v_mul_f32_e32 v151, v155, v155
	v_pk_add_f32 v[152:153], v[24:25], v[152:153]
	v_fmac_f32_e32 v150, v144, v144
	v_fmac_f32_e32 v151, v154, v154
	v_lshlrev_b32_e32 v146, 16, v147
	v_and_b32_e32 v147, 0xffff0000, v147
	v_add_f32_e32 v150, v150, v151
	v_mul_f32_e32 v151, v153, v153
	v_pk_add_f32 v[146:147], v[26:27], v[146:147]
	v_fmac_f32_e32 v151, v152, v152
	v_add_f32_e32 v150, v151, v150
	v_mul_f32_e32 v151, v147, v147
	v_fmac_f32_e32 v151, v146, v146
	v_add_f32_e32 v151, v151, v150
	v_mov_b32_e32 v166, v151
	s_nop 1
	v_permlane16_swap_b32_e32 v166, v151
	v_cvt_pk_bf16_f32 v150, v144, v145
	v_cvt_pk_bf16_f32 v152, v152, v153
	v_cvt_pk_bf16_f32 v153, v146, v147
	s_waitcnt lgkmcnt(0)
	v_add_f32_e32 v144, v151, v166
	v_mov_b32_e32 v145, v144
	s_nop 1
	v_permlane32_swap_b32_e32 v145, v144
	v_cvt_pk_bf16_f32 v151, v154, v155
	global_store_dwordx4 v[164:165], v[150:153], off offset:256
	s_and_saveexec_b64 s[72:73], s[6:7]
	s_cbranch_execz .LBB0_569
	s_lshl_b32 s74, s19, 3
	s_ashr_i32 s75, s74, 31
	s_waitcnt lgkmcnt(0)
	v_add_f32_e32 v146, v144, v145
	v_lshl_add_u64 v[144:145], s[74:75], 2, v[148:149]
	s_lshl_b32 s50, s37, 2
	v_lshl_add_u64 v[144:145], v[144:145], 0, s[50:51]
	global_store_dword v[144:145], v146, off offset:16
.LBB0_569:
	s_or_b64 exec, exec, s[72:73]
	s_waitcnt vmcnt(7)
	v_lshlrev_b32_e32 v144, 16, v140
	s_waitcnt lgkmcnt(0)
	v_and_b32_e32 v145, 0xffff0000, v140
	v_lshlrev_b32_e32 v140, 16, v141
	v_and_b32_e32 v141, 0xffff0000, v141
	v_pk_add_f32 v[148:149], v[38:39], v[140:141]
	v_pk_add_f32 v[144:145], v[36:37], v[144:145]
	v_lshlrev_b32_e32 v146, 16, v142
	v_and_b32_e32 v147, 0xffff0000, v142
	v_mul_f32_e32 v140, v145, v145
	v_mul_f32_e32 v141, v149, v149
	v_pk_add_f32 v[146:147], v[32:33], v[146:147]
	v_fmac_f32_e32 v140, v144, v144
	v_fmac_f32_e32 v141, v148, v148
	v_lshlrev_b32_e32 v142, 16, v143
	v_and_b32_e32 v143, 0xffff0000, v143
	v_add_f32_e32 v140, v140, v141
	v_mul_f32_e32 v141, v147, v147
	v_pk_add_f32 v[150:151], v[34:35], v[142:143]
	v_fmac_f32_e32 v141, v146, v146
	v_add_f32_e32 v140, v141, v140
	v_mul_f32_e32 v141, v151, v151
	v_fmac_f32_e32 v141, v150, v150
	v_add_f32_e32 v142, v141, v140
	v_mov_b32_e32 v143, v142
	s_nop 1
	v_permlane16_swap_b32_e32 v143, v142
	v_lshlrev_b64 v[140:141], 8, v[162:163]
	v_lshl_add_u64 v[140:141], s[26:27], 0, v[140:141]
	v_cvt_pk_bf16_f32 v144, v144, v145
	v_cvt_pk_bf16_f32 v145, v148, v149
	s_waitcnt lgkmcnt(0)
	v_add_f32_e32 v142, v142, v143
	v_mov_b32_e32 v143, v142
	s_nop 1
	v_permlane32_swap_b32_e32 v143, v142
	v_cvt_pk_bf16_f32 v146, v146, v147
	v_cvt_pk_bf16_f32 v147, v150, v151
	global_store_dwordx4 v[160:161], v[144:147], off
	s_and_saveexec_b64 s[72:73], s[6:7]
	s_cbranch_execz .LBB0_571
	s_lshl_b32 s74, s19, 3
	s_ashr_i32 s75, s74, 31
	s_waitcnt lgkmcnt(0)
	v_add_f32_e32 v144, v142, v143
	v_lshl_add_u64 v[142:143], s[74:75], 2, v[140:141]
	s_lshl_b32 s50, s37, 2
	v_lshl_add_u64 v[142:143], v[142:143], 0, s[50:51]
	global_store_dword v[142:143], v144, off
.LBB0_571:
	s_or_b64 exec, exec, s[72:73]
	s_waitcnt vmcnt(7)
	v_lshlrev_b32_e32 v142, 16, v136
	s_waitcnt lgkmcnt(0)
	v_and_b32_e32 v143, 0xffff0000, v136
	v_lshlrev_b32_e32 v136, 16, v137
	v_and_b32_e32 v137, 0xffff0000, v137
	v_pk_add_f32 v[146:147], v[14:15], v[136:137]
	v_pk_add_f32 v[136:137], v[12:13], v[142:143]
	v_lshlrev_b32_e32 v144, 16, v138
	v_and_b32_e32 v145, 0xffff0000, v138
	v_mul_f32_e32 v142, v137, v137
	v_mul_f32_e32 v143, v147, v147
	v_pk_add_f32 v[144:145], v[8:9], v[144:145]
	v_fmac_f32_e32 v142, v136, v136
	v_fmac_f32_e32 v143, v146, v146
	v_lshlrev_b32_e32 v138, 16, v139
	v_and_b32_e32 v139, 0xffff0000, v139
	v_add_f32_e32 v142, v142, v143
	v_mul_f32_e32 v143, v145, v145
	v_pk_add_f32 v[138:139], v[10:11], v[138:139]
	v_fmac_f32_e32 v143, v144, v144
	v_add_f32_e32 v142, v143, v142
	v_mul_f32_e32 v143, v139, v139
	v_fmac_f32_e32 v143, v138, v138
	v_add_f32_e32 v143, v143, v142
	v_mov_b32_e32 v148, v143
	s_nop 1
	v_permlane16_swap_b32_e32 v148, v143
	v_cvt_pk_bf16_f32 v142, v136, v137
	v_cvt_pk_bf16_f32 v144, v144, v145
	v_cvt_pk_bf16_f32 v145, v138, v139
	s_waitcnt lgkmcnt(0)
	v_add_f32_e32 v136, v143, v148
	v_mov_b32_e32 v137, v136
	s_nop 1
	v_permlane32_swap_b32_e32 v137, v136
	v_cvt_pk_bf16_f32 v143, v146, v147
	global_store_dwordx4 v[160:161], v[142:145], off offset:256
	s_and_saveexec_b64 s[72:73], s[6:7]
	s_cbranch_execz .LBB0_573
	s_lshl_b32 s74, s19, 3
	s_ashr_i32 s75, s74, 31
	s_waitcnt lgkmcnt(0)
	v_add_f32_e32 v138, v136, v137
	v_lshl_add_u64 v[136:137], s[74:75], 2, v[140:141]
	s_lshl_b32 s50, s37, 2
	v_lshl_add_u64 v[136:137], v[136:137], 0, s[50:51]
	global_store_dword v[136:137], v138, off offset:16
.LBB0_573:
	s_or_b64 exec, exec, s[72:73]
	s_waitcnt vmcnt(7)
	v_lshlrev_b32_e32 v136, 16, v132
	s_waitcnt lgkmcnt(0)
	v_and_b32_e32 v137, 0xffff0000, v132
	v_lshlrev_b32_e32 v132, 16, v133
	v_and_b32_e32 v133, 0xffff0000, v133
	v_pk_add_f32 v[140:141], v[22:23], v[132:133]
	v_pk_add_f32 v[136:137], v[20:21], v[136:137]
	v_lshlrev_b32_e32 v138, 16, v134
	v_and_b32_e32 v139, 0xffff0000, v134
	v_mul_f32_e32 v132, v137, v137
	v_mul_f32_e32 v133, v141, v141
	v_pk_add_f32 v[138:139], v[16:17], v[138:139]
	v_fmac_f32_e32 v132, v136, v136
	v_fmac_f32_e32 v133, v140, v140
	v_lshlrev_b32_e32 v134, 16, v135
	v_and_b32_e32 v135, 0xffff0000, v135
	v_add_f32_e32 v132, v132, v133
	v_mul_f32_e32 v133, v139, v139
	v_pk_add_f32 v[142:143], v[18:19], v[134:135]
	v_fmac_f32_e32 v133, v138, v138
	v_add_f32_e32 v132, v133, v132
	v_mul_f32_e32 v133, v143, v143
	v_fmac_f32_e32 v133, v142, v142
	v_add_f32_e32 v134, v133, v132
	v_mov_b32_e32 v135, v134
	s_nop 1
	v_permlane16_swap_b32_e32 v135, v134
	v_lshlrev_b64 v[132:133], 8, v[158:159]
	v_lshl_add_u64 v[132:133], s[26:27], 0, v[132:133]
	v_cvt_pk_bf16_f32 v136, v136, v137
	v_cvt_pk_bf16_f32 v137, v140, v141
	s_waitcnt lgkmcnt(0)
	v_add_f32_e32 v134, v134, v135
	v_mov_b32_e32 v135, v134
	s_nop 1
	v_permlane32_swap_b32_e32 v135, v134
	v_cvt_pk_bf16_f32 v138, v138, v139
	v_cvt_pk_bf16_f32 v139, v142, v143
	global_store_dwordx4 v[156:157], v[136:139], off
	s_and_saveexec_b64 s[72:73], s[6:7]
	s_cbranch_execz .LBB0_575
	s_lshl_b32 s74, s19, 3
	s_ashr_i32 s75, s74, 31
	s_waitcnt lgkmcnt(0)
	v_add_f32_e32 v136, v134, v135
	v_lshl_add_u64 v[134:135], s[74:75], 2, v[132:133]
	s_lshl_b32 s50, s37, 2
	v_lshl_add_u64 v[134:135], v[134:135], 0, s[50:51]
	global_store_dword v[134:135], v136, off
.LBB0_575:
	s_or_b64 exec, exec, s[72:73]
	s_waitcnt vmcnt(7)
	v_lshlrev_b32_e32 v134, 16, v128
	s_waitcnt lgkmcnt(0)
	v_and_b32_e32 v135, 0xffff0000, v128
	v_lshlrev_b32_e32 v128, 16, v129
	v_and_b32_e32 v129, 0xffff0000, v129
	v_pk_add_f32 v[138:139], v[6:7], v[128:129]
	v_pk_add_f32 v[128:129], v[4:5], v[134:135]
	v_lshlrev_b32_e32 v136, 16, v130
	v_and_b32_e32 v137, 0xffff0000, v130
	v_mul_f32_e32 v134, v129, v129
	v_mul_f32_e32 v135, v139, v139
	v_pk_add_f32 v[136:137], v[0:1], v[136:137]
	v_fmac_f32_e32 v134, v128, v128
	v_fmac_f32_e32 v135, v138, v138
	v_lshlrev_b32_e32 v130, 16, v131
	v_and_b32_e32 v131, 0xffff0000, v131
	v_add_f32_e32 v134, v134, v135
	v_mul_f32_e32 v135, v137, v137
	v_pk_add_f32 v[130:131], v[2:3], v[130:131]
	v_fmac_f32_e32 v135, v136, v136
	v_add_f32_e32 v134, v135, v134
	v_mul_f32_e32 v135, v131, v131
	v_fmac_f32_e32 v135, v130, v130
	v_add_f32_e32 v135, v135, v134
	v_mov_b32_e32 v140, v135
	s_nop 1
	v_permlane16_swap_b32_e32 v140, v135
	v_cvt_pk_bf16_f32 v134, v128, v129
	v_cvt_pk_bf16_f32 v136, v136, v137
	v_cvt_pk_bf16_f32 v137, v130, v131
	s_waitcnt lgkmcnt(0)
	v_add_f32_e32 v128, v135, v140
	v_mov_b32_e32 v129, v128
	s_nop 1
	v_permlane32_swap_b32_e32 v129, v128
	v_cvt_pk_bf16_f32 v135, v138, v139
	global_store_dwordx4 v[156:157], v[134:137], off offset:256
	s_and_saveexec_b64 s[72:73], s[6:7]
	s_cbranch_execz .LBB0_577
	s_lshl_b32 s74, s19, 3
	s_ashr_i32 s75, s74, 31
	s_waitcnt lgkmcnt(0)
	v_add_f32_e32 v130, v128, v129
	v_lshl_add_u64 v[128:129], s[74:75], 2, v[132:133]
	s_lshl_b32 s50, s37, 2
	v_lshl_add_u64 v[128:129], v[128:129], 0, s[50:51]
	global_store_dword v[128:129], v130, off offset:16

.LBB0_628:
	s_or_b64 exec, exec, s[72:73]
	v_lshl_add_u64 v[132:133], v[210:211], 2, v[128:129]
	global_load_dwordx4 v[152:155], v[132:133], off offset:16 nt
	global_load_dwordx4 v[160:163], v[132:133], off nt
	global_load_dwordx4 v[128:131], v[132:133], off offset:528 nt
	s_nop 0
	global_load_dwordx4 v[132:135], v[132:133], off offset:512 nt
	v_and_b32_e32 v213, 64, v231
	v_xor_b32_e32 v192, 16, v231
	v_add_u32_e32 v213, 64, v213
	v_cmp_lt_i32_e32 vcc, v192, v213
	s_waitcnt vmcnt(0)
	v_pk_add_f32 v[190:191], v[126:127], v[190:191]
	v_pk_add_f32 v[188:189], v[124:125], v[188:189]
	v_cndmask_b32_e32 v192, v231, v192, vcc
	v_lshlrev_b32_e32 v241, 2, v192
	v_xor_b32_e32 v192, 32, v231
	v_cmp_lt_i32_e32 vcc, v192, v213
	v_ashrrev_i32_e32 v213, 31, v212
	v_lshlrev_b64 v[220:221], 12, v[212:213]
	v_cndmask_b32_e32 v192, v231, v192, vcc
	v_lshlrev_b32_e32 v242, 2, v192
	v_lshlrev_b64 v[248:249], 8, v[212:213]
	v_mul_f32_e32 v192, v189, v189
	v_mul_f32_e32 v213, v191, v191
	v_pk_add_f32 v[184:185], v[120:121], v[184:185]
	v_fmac_f32_e32 v192, v188, v188
	v_fmac_f32_e32 v213, v190, v190
	v_add_f32_e32 v192, v192, v213
	v_mul_f32_e32 v213, v185, v185
	v_pk_add_f32 v[186:187], v[122:123], v[186:187]
	v_fmac_f32_e32 v213, v184, v184
	v_add_f32_e32 v192, v192, v213
	v_mul_f32_e32 v213, v187, v187
	v_fmac_f32_e32 v213, v186, v186
	v_add_f32_e32 v192, v213, v192
	v_mov_b32_e32 v213, v192
	s_nop 1
	v_permlane16_swap_b32_e32 v213, v192
	v_cvt_pk_bf16_f32 v244, v188, v189
	v_cvt_pk_bf16_f32 v246, v184, v185
	v_lshl_add_u64 v[184:185], s[24:25], 0, v[220:221]
	v_cvt_pk_bf16_f32 v245, v190, v191
	s_waitcnt lgkmcnt(0)
	v_add_f32_e32 v188, v192, v213
	v_mov_b32_e32 v189, v188
	s_nop 1
	v_permlane32_swap_b32_e32 v189, v188
	v_cvt_pk_bf16_f32 v247, v186, v187
	v_lshl_add_u64 v[186:187], v[210:211], 1, v[184:185]
	v_lshl_add_u64 v[184:185], s[26:27], 0, v[248:249]
	global_store_dwordx4 v[186:187], v[244:247], off
	s_and_saveexec_b64 s[72:73], s[6:7]
	s_cbranch_execz .LBB0_630
	s_lshl_b32 s74, s19, 3
	s_ashr_i32 s75, s74, 31
	s_waitcnt lgkmcnt(0)
	v_add_f32_e32 v190, v188, v189
	v_lshl_add_u64 v[188:189], s[74:75], 2, v[184:185]
	s_lshl_b32 s50, s37, 2
	v_lshl_add_u64 v[188:189], v[188:189], 0, s[50:51]
	global_store_dword v[188:189], v190, off
.LBB0_630:
	s_or_b64 exec, exec, s[72:73]
	v_pk_add_f32 v[166:167], v[110:111], v[166:167]
	v_pk_add_f32 v[164:165], v[108:109], v[164:165]
	s_waitcnt lgkmcnt(0)
	v_pk_add_f32 v[188:189], v[104:105], v[156:157]
	v_mul_f32_e32 v156, v165, v165
	v_mul_f32_e32 v157, v167, v167
	v_fmac_f32_e32 v156, v164, v164
	v_fmac_f32_e32 v157, v166, v166
	v_add_f32_e32 v156, v156, v157
	v_mul_f32_e32 v157, v189, v189
	v_pk_add_f32 v[158:159], v[106:107], v[158:159]
	v_fmac_f32_e32 v157, v188, v188
	v_add_f32_e32 v156, v156, v157
	v_mul_f32_e32 v157, v159, v159
	v_fmac_f32_e32 v157, v158, v158
	v_add_f32_e32 v156, v157, v156
	v_mov_b32_e32 v157, v156
	s_nop 1
	v_permlane16_swap_b32_e32 v157, v156
	v_cvt_pk_bf16_f32 v164, v164, v165
	v_cvt_pk_bf16_f32 v165, v166, v167
	v_cvt_pk_bf16_f32 v166, v188, v189
	v_cvt_pk_bf16_f32 v167, v158, v159
	s_waitcnt lgkmcnt(0)
	v_add_f32_e32 v156, v156, v157
	v_mov_b32_e32 v157, v156
	s_nop 1
	v_permlane32_swap_b32_e32 v157, v156
	global_store_dwordx4 v[186:187], v[164:167], off offset:256
	s_and_saveexec_b64 s[72:73], s[6:7]
	s_cbranch_execz .LBB0_632
	s_lshl_b32 s74, s19, 3
	s_ashr_i32 s75, s74, 31
	s_waitcnt lgkmcnt(0)
	v_add_f32_e32 v158, v156, v157
	v_lshl_add_u64 v[156:157], s[74:75], 2, v[184:185]
	s_lshl_b32 s50, s37, 2
	v_lshl_add_u64 v[156:157], v[156:157], 0, s[50:51]
	global_store_dword v[156:157], v158, off offset:16
.LBB0_632:
	s_or_b64 exec, exec, s[72:73]
	v_pk_add_f32 v[158:159], v[118:119], v[182:183]
	v_pk_add_f32 v[164:165], v[116:117], v[180:181]
	v_pk_add_f32 v[180:181], v[114:115], v[178:179]
	v_pk_add_f32 v[178:179], v[112:113], v[176:177]
	v_mul_f32_e32 v176, v165, v165
	v_mul_f32_e32 v177, v159, v159
	v_fmac_f32_e32 v176, v164, v164
	v_fmac_f32_e32 v177, v158, v158
	v_add_f32_e32 v176, v176, v177
	v_mul_f32_e32 v177, v179, v179
	v_fmac_f32_e32 v177, v178, v178
	v_add_f32_e32 v176, v176, v177
	v_mul_f32_e32 v177, v181, v181
	v_fmac_f32_e32 v177, v180, v180
	v_add_f32_e32 v182, v177, v176
	v_mov_b32_e32 v183, v182
	s_nop 1
	v_permlane16_swap_b32_e32 v183, v182
	v_cvt_pk_bf16_f32 v176, v164, v165
	v_ashrrev_i32_e32 v219, 31, v218
	s_waitcnt lgkmcnt(0)
	v_lshlrev_b64 v[156:157], 12, v[218:219]
	v_lshlrev_b64 v[166:167], 8, v[218:219]
	s_waitcnt lgkmcnt(0)
	v_add_f32_e32 v164, v182, v183
	v_mov_b32_e32 v165, v164
	s_nop 1
	v_permlane32_swap_b32_e32 v165, v164
	v_lshl_add_u64 v[156:157], s[24:25], 0, v[156:157]
	v_cvt_pk_bf16_f32 v177, v158, v159
	v_cvt_pk_bf16_f32 v178, v178, v179
	v_cvt_pk_bf16_f32 v179, v180, v181
	v_lshl_add_u64 v[158:159], v[210:211], 1, v[156:157]
	v_lshl_add_u64 v[156:157], s[26:27], 0, v[166:167]
	global_store_dwordx4 v[158:159], v[176:179], off
	s_and_saveexec_b64 s[72:73], s[6:7]
	s_cbranch_execz .LBB0_634
	s_lshl_b32 s74, s19, 3
	s_ashr_i32 s75, s74, 31
	s_waitcnt lgkmcnt(0)
	v_add_f32_e32 v166, v164, v165
	v_lshl_add_u64 v[164:165], s[74:75], 2, v[156:157]
	s_lshl_b32 s50, s37, 2
	v_lshl_add_u64 v[164:165], v[164:165], 0, s[50:51]
	global_store_dword v[164:165], v166, off
.LBB0_634:
	s_or_b64 exec, exec, s[72:73]
	v_pk_add_f32 v[150:151], v[94:95], v[150:151]
	v_pk_add_f32 v[148:149], v[92:93], v[148:149]
	v_pk_add_f32 v[166:167], v[88:89], v[144:145]
	v_mul_f32_e32 v144, v149, v149
	v_mul_f32_e32 v145, v151, v151
	v_fmac_f32_e32 v144, v148, v148
	v_fmac_f32_e32 v145, v150, v150
	v_add_f32_e32 v144, v144, v145
	v_mul_f32_e32 v145, v167, v167
	s_waitcnt lgkmcnt(0)
	v_pk_add_f32 v[164:165], v[90:91], v[146:147]
	v_fmac_f32_e32 v145, v166, v166
	v_add_f32_e32 v144, v144, v145
	v_mul_f32_e32 v145, v165, v165
	v_fmac_f32_e32 v145, v164, v164
	v_add_f32_e32 v144, v145, v144
	v_mov_b32_e32 v145, v144
	s_nop 1
	v_permlane16_swap_b32_e32 v145, v144
	v_cvt_pk_bf16_f32 v146, v148, v149
	v_cvt_pk_bf16_f32 v147, v150, v151
	v_cvt_pk_bf16_f32 v148, v166, v167
	v_cvt_pk_bf16_f32 v149, v164, v165
	s_waitcnt lgkmcnt(0)
	v_add_f32_e32 v144, v144, v145
	v_mov_b32_e32 v145, v144
	s_nop 1
	v_permlane32_swap_b32_e32 v145, v144
	global_store_dwordx4 v[158:159], v[146:149], off offset:256
	s_and_saveexec_b64 s[72:73], s[6:7]
	s_cbranch_execz .LBB0_636
	s_lshl_b32 s74, s19, 3
	s_ashr_i32 s75, s74, 31
	s_waitcnt lgkmcnt(0)
	v_add_f32_e32 v146, v144, v145
	v_lshl_add_u64 v[144:145], s[74:75], 2, v[156:157]
	s_lshl_b32 s50, s37, 2
	v_lshl_add_u64 v[144:145], v[144:145], 0, s[50:51]
	global_store_dword v[144:145], v146, off offset:16
.LBB0_636:
	s_or_b64 exec, exec, s[72:73]
	v_pk_add_f32 v[146:147], v[102:103], v[174:175]
	v_pk_add_f32 v[148:149], v[100:101], v[172:173]
	v_mul_f32_e32 v157, v147, v147
	v_mul_f32_e32 v156, v149, v149
	v_pk_add_f32 v[158:159], v[96:97], v[168:169]
	v_fmac_f32_e32 v156, v148, v148
	v_fmac_f32_e32 v157, v146, v146
	v_add_f32_e32 v156, v156, v157
	v_mul_f32_e32 v157, v159, v159
	v_pk_add_f32 v[164:165], v[98:99], v[170:171]
	v_fmac_f32_e32 v157, v158, v158
	v_add_f32_e32 v156, v156, v157
	v_mul_f32_e32 v157, v165, v165
	v_fmac_f32_e32 v157, v164, v164
	v_add_f32_e32 v166, v157, v156
	v_mov_b32_e32 v167, v166
	s_nop 1
	v_permlane16_swap_b32_e32 v167, v166
	v_cvt_pk_bf16_f32 v156, v148, v149
	v_ashrrev_i32_e32 v217, 31, v216
	s_waitcnt lgkmcnt(0)
	v_lshlrev_b64 v[144:145], 12, v[216:217]
	v_lshlrev_b64 v[150:151], 8, v[216:217]
	s_waitcnt lgkmcnt(0)
	v_add_f32_e32 v148, v166, v167
	v_mov_b32_e32 v149, v148
	s_nop 1
	v_permlane32_swap_b32_e32 v149, v148
	v_lshl_add_u64 v[144:145], s[24:25], 0, v[144:145]
	v_cvt_pk_bf16_f32 v157, v146, v147
	v_cvt_pk_bf16_f32 v158, v158, v159
	v_cvt_pk_bf16_f32 v159, v164, v165
	v_lshl_add_u64 v[146:147], v[210:211], 1, v[144:145]
	v_lshl_add_u64 v[144:145], s[26:27], 0, v[150:151]
	global_store_dwordx4 v[146:147], v[156:159], off
	s_and_saveexec_b64 s[72:73], s[6:7]
	s_cbranch_execz .LBB0_638
	s_lshl_b32 s74, s19, 3
	s_ashr_i32 s75, s74, 31
	s_waitcnt lgkmcnt(0)
	v_add_f32_e32 v150, v148, v149
	v_lshl_add_u64 v[148:149], s[74:75], 2, v[144:145]
	s_lshl_b32 s50, s37, 2
	v_lshl_add_u64 v[148:149], v[148:149], 0, s[50:51]
	global_store_dword v[148:149], v150, off
.LBB0_638:
	s_or_b64 exec, exec, s[72:73]
	v_pk_add_f32 v[142:143], v[78:79], v[142:143]
	v_pk_add_f32 v[140:141], v[76:77], v[140:141]
	v_pk_add_f32 v[150:151], v[72:73], v[136:137]
	v_mul_f32_e32 v136, v141, v141
	v_mul_f32_e32 v137, v143, v143
	v_fmac_f32_e32 v136, v140, v140
	v_fmac_f32_e32 v137, v142, v142
	v_add_f32_e32 v136, v136, v137
	v_mul_f32_e32 v137, v151, v151
	s_waitcnt lgkmcnt(0)
	v_pk_add_f32 v[148:149], v[74:75], v[138:139]
	v_fmac_f32_e32 v137, v150, v150
	v_add_f32_e32 v136, v136, v137
	v_mul_f32_e32 v137, v149, v149
	v_fmac_f32_e32 v137, v148, v148
	v_add_f32_e32 v136, v137, v136
	v_mov_b32_e32 v137, v136
	s_nop 1
	v_permlane16_swap_b32_e32 v137, v136
	v_cvt_pk_bf16_f32 v138, v140, v141
	v_cvt_pk_bf16_f32 v139, v142, v143
	v_cvt_pk_bf16_f32 v140, v150, v151
	v_cvt_pk_bf16_f32 v141, v148, v149
	s_waitcnt lgkmcnt(0)
	v_add_f32_e32 v136, v136, v137
	v_mov_b32_e32 v137, v136
	s_nop 1
	v_permlane32_swap_b32_e32 v137, v136
	global_store_dwordx4 v[146:147], v[138:141], off offset:256
	s_and_saveexec_b64 s[72:73], s[6:7]
	s_cbranch_execz .LBB0_640
	s_lshl_b32 s74, s19, 3
	s_ashr_i32 s75, s74, 31
	s_waitcnt lgkmcnt(0)
	v_add_f32_e32 v138, v136, v137
	v_lshl_add_u64 v[136:137], s[74:75], 2, v[144:145]
	s_lshl_b32 s50, s37, 2
	v_lshl_add_u64 v[136:137], v[136:137], 0, s[50:51]
	global_store_dword v[136:137], v138, off offset:16
.LBB0_640:
	s_or_b64 exec, exec, s[72:73]
	v_pk_add_f32 v[138:139], v[86:87], v[162:163]
	v_pk_add_f32 v[140:141], v[84:85], v[160:161]
	v_mul_f32_e32 v143, v139, v139
	v_mul_f32_e32 v142, v141, v141
	v_pk_add_f32 v[144:145], v[80:81], v[152:153]
	v_fmac_f32_e32 v142, v140, v140
	v_fmac_f32_e32 v143, v138, v138
	v_add_f32_e32 v142, v142, v143
	v_mul_f32_e32 v143, v145, v145
	v_pk_add_f32 v[148:149], v[82:83], v[154:155]
	v_fmac_f32_e32 v143, v144, v144
	v_add_f32_e32 v142, v142, v143
	v_mul_f32_e32 v143, v149, v149
	v_fmac_f32_e32 v143, v148, v148
	v_add_f32_e32 v150, v143, v142
	v_mov_b32_e32 v151, v150
	s_nop 1
	v_permlane16_swap_b32_e32 v151, v150
	v_cvt_pk_bf16_f32 v142, v140, v141
	v_ashrrev_i32_e32 v215, 31, v214
	s_waitcnt lgkmcnt(0)
	v_lshlrev_b64 v[136:137], 12, v[214:215]
	v_lshlrev_b64 v[146:147], 8, v[214:215]
	s_waitcnt lgkmcnt(0)
	v_add_f32_e32 v140, v150, v151
	v_mov_b32_e32 v141, v140
	s_nop 1
	v_permlane32_swap_b32_e32 v141, v140
	v_lshl_add_u64 v[136:137], s[24:25], 0, v[136:137]
	v_cvt_pk_bf16_f32 v143, v138, v139
	v_cvt_pk_bf16_f32 v144, v144, v145
	v_cvt_pk_bf16_f32 v145, v148, v149
	v_lshl_add_u64 v[138:139], v[210:211], 1, v[136:137]
	v_lshl_add_u64 v[136:137], s[26:27], 0, v[146:147]
	global_store_dwordx4 v[138:139], v[142:145], off
	s_and_saveexec_b64 s[72:73], s[6:7]
	s_cbranch_execz .LBB0_642
	s_lshl_b32 s74, s19, 3
	s_ashr_i32 s75, s74, 31
	s_waitcnt lgkmcnt(0)
	v_add_f32_e32 v142, v140, v141
	v_lshl_add_u64 v[140:141], s[74:75], 2, v[136:137]
	s_lshl_b32 s50, s37, 2
	v_lshl_add_u64 v[140:141], v[140:141], 0, s[50:51]
	global_store_dword v[140:141], v142, off
.LBB0_642:
	s_or_b64 exec, exec, s[72:73]
	v_pk_add_f32 v[134:135], v[70:71], v[134:135]
	v_pk_add_f32 v[132:133], v[68:69], v[132:133]
	v_pk_add_f32 v[142:143], v[64:65], v[128:129]
	v_mul_f32_e32 v128, v133, v133
	v_mul_f32_e32 v129, v135, v135
	v_fmac_f32_e32 v128, v132, v132
	v_fmac_f32_e32 v129, v134, v134
	v_add_f32_e32 v128, v128, v129
	v_mul_f32_e32 v129, v143, v143
	s_waitcnt lgkmcnt(0)
	v_pk_add_f32 v[140:141], v[66:67], v[130:131]
	v_fmac_f32_e32 v129, v142, v142
	v_add_f32_e32 v128, v128, v129
	v_mul_f32_e32 v129, v141, v141
	v_fmac_f32_e32 v129, v140, v140
	v_add_f32_e32 v128, v129, v128
	v_mov_b32_e32 v129, v128
	s_nop 1
	v_permlane16_swap_b32_e32 v129, v128
	v_cvt_pk_bf16_f32 v130, v132, v133
	v_cvt_pk_bf16_f32 v131, v134, v135
	v_cvt_pk_bf16_f32 v132, v142, v143
	v_cvt_pk_bf16_f32 v133, v140, v141
	s_waitcnt lgkmcnt(0)
	v_add_f32_e32 v128, v128, v129
	v_mov_b32_e32 v129, v128
	s_nop 1
	v_permlane32_swap_b32_e32 v129, v128
	global_store_dwordx4 v[138:139], v[130:133], off offset:256
	s_and_saveexec_b64 s[72:73], s[6:7]
	s_cbranch_execz .LBB0_644
	s_lshl_b32 s74, s19, 3
	s_ashr_i32 s75, s74, 31
	s_waitcnt lgkmcnt(0)
	v_add_f32_e32 v130, v128, v129
	v_lshl_add_u64 v[128:129], s[74:75], 2, v[136:137]
	s_lshl_b32 s50, s37, 2
	v_lshl_add_u64 v[128:129], v[128:129], 0, s[50:51]
	global_store_dword v[128:129], v130, off offset:16

.LBB0_692:
	s_or_b64 exec, exec, s[72:73]
	v_lshl_add_u64 v[132:133], v[210:211], 2, v[128:129]
	global_load_dwordx4 v[160:163], v[132:133], off offset:16 nt
	global_load_dwordx4 v[164:167], v[132:133], off nt
	global_load_dwordx4 v[128:131], v[132:133], off offset:528 nt
	s_nop 0
	global_load_dwordx4 v[132:135], v[132:133], off offset:512 nt
	s_waitcnt vmcnt(14)
	v_pk_add_f32 v[190:191], v[62:63], v[190:191]
	v_pk_add_f32 v[188:189], v[60:61], v[188:189]
	v_mul_f32_e32 v215, v191, v191
	v_mul_f32_e32 v192, v189, v189
	v_pk_add_f32 v[184:185], v[56:57], v[184:185]
	v_fmac_f32_e32 v192, v188, v188
	v_fmac_f32_e32 v215, v190, v190
	v_add_f32_e32 v192, v192, v215
	v_mul_f32_e32 v215, v185, v185
	v_pk_add_f32 v[186:187], v[58:59], v[186:187]
	v_fmac_f32_e32 v215, v184, v184
	v_add_f32_e32 v192, v192, v215
	v_mul_f32_e32 v215, v187, v187
	v_fmac_f32_e32 v215, v186, v186
	v_add_f32_e32 v192, v215, v192
	v_mov_b32_e32 v215, v192
	s_nop 1
	v_permlane16_swap_b32_e32 v215, v192
	v_cvt_pk_bf16_f32 v244, v188, v189
	v_ashrrev_i32_e32 v221, 31, v220
	v_lshlrev_b64 v[212:213], 12, v[220:221]
	v_lshlrev_b64 v[220:221], 8, v[220:221]
	s_waitcnt lgkmcnt(0)
	v_add_f32_e32 v188, v192, v215
	v_mov_b32_e32 v189, v188
	s_nop 1
	v_permlane32_swap_b32_e32 v189, v188
	v_cvt_pk_bf16_f32 v246, v184, v185
	v_lshl_add_u64 v[184:185], s[24:25], 0, v[212:213]
	v_cvt_pk_bf16_f32 v245, v190, v191
	v_cvt_pk_bf16_f32 v247, v186, v187
	v_lshl_add_u64 v[186:187], v[210:211], 1, v[184:185]
	v_lshl_add_u64 v[184:185], s[26:27], 0, v[220:221]
	global_store_dwordx4 v[186:187], v[244:247], off
	s_and_saveexec_b64 s[72:73], s[6:7]
	s_cbranch_execz .LBB0_694
	s_lshl_b32 s74, s19, 3
	s_ashr_i32 s75, s74, 31
	s_waitcnt lgkmcnt(0)
	v_add_f32_e32 v190, v188, v189
	v_lshl_add_u64 v[188:189], s[74:75], 2, v[184:185]
	s_lshl_b32 s50, s37, 2
	v_lshl_add_u64 v[188:189], v[188:189], 0, s[50:51]
	global_store_dword v[188:189], v190, off
.LBB0_694:
	s_or_b64 exec, exec, s[72:73]
	s_waitcnt vmcnt(13)
	v_pk_add_f32 v[158:159], v[46:47], v[158:159]
	v_pk_add_f32 v[156:157], v[44:45], v[156:157]
	v_pk_add_f32 v[190:191], v[40:41], v[152:153]
	v_mul_f32_e32 v152, v157, v157
	v_mul_f32_e32 v153, v159, v159
	v_fmac_f32_e32 v152, v156, v156
	v_fmac_f32_e32 v153, v158, v158
	v_add_f32_e32 v152, v152, v153
	v_mul_f32_e32 v153, v191, v191
	s_waitcnt lgkmcnt(0)
	v_pk_add_f32 v[188:189], v[42:43], v[154:155]
	v_fmac_f32_e32 v153, v190, v190
	v_add_f32_e32 v152, v152, v153
	v_mul_f32_e32 v153, v189, v189
	v_fmac_f32_e32 v153, v188, v188
	v_add_f32_e32 v152, v153, v152
	v_mov_b32_e32 v153, v152
	s_nop 1
	v_permlane16_swap_b32_e32 v153, v152
	v_cvt_pk_bf16_f32 v154, v156, v157
	v_cvt_pk_bf16_f32 v155, v158, v159
	v_cvt_pk_bf16_f32 v156, v190, v191
	v_cvt_pk_bf16_f32 v157, v188, v189
	s_waitcnt lgkmcnt(0)
	v_add_f32_e32 v152, v152, v153
	v_mov_b32_e32 v153, v152
	s_nop 1
	v_permlane32_swap_b32_e32 v153, v152
	global_store_dwordx4 v[186:187], v[154:157], off offset:256
	s_and_saveexec_b64 s[72:73], s[6:7]
	s_cbranch_execz .LBB0_696
	s_lshl_b32 s74, s19, 3
	s_ashr_i32 s75, s74, 31
	s_waitcnt lgkmcnt(0)
	v_add_f32_e32 v154, v152, v153
	v_lshl_add_u64 v[152:153], s[74:75], 2, v[184:185]
	s_lshl_b32 s50, s37, 2
	v_lshl_add_u64 v[152:153], v[152:153], 0, s[50:51]
	global_store_dword v[152:153], v154, off offset:16
.LBB0_696:
	s_or_b64 exec, exec, s[72:73]
	s_waitcnt vmcnt(12)
	v_pk_add_f32 v[154:155], v[54:55], v[182:183]
	v_pk_add_f32 v[156:157], v[52:53], v[180:181]
	v_pk_add_f32 v[180:181], v[50:51], v[178:179]
	v_pk_add_f32 v[178:179], v[48:49], v[176:177]
	v_mul_f32_e32 v176, v157, v157
	v_mul_f32_e32 v177, v155, v155
	v_fmac_f32_e32 v176, v156, v156
	v_fmac_f32_e32 v177, v154, v154
	v_add_f32_e32 v176, v176, v177
	v_mul_f32_e32 v177, v179, v179
	v_fmac_f32_e32 v177, v178, v178
	v_add_f32_e32 v176, v176, v177
	v_mul_f32_e32 v177, v181, v181
	v_fmac_f32_e32 v177, v180, v180
	v_add_f32_e32 v182, v177, v176
	v_mov_b32_e32 v183, v182
	s_nop 1
	v_permlane16_swap_b32_e32 v183, v182
	v_cvt_pk_bf16_f32 v176, v156, v157
	v_ashrrev_i32_e32 v219, 31, v218
	s_waitcnt lgkmcnt(0)
	v_lshlrev_b64 v[152:153], 12, v[218:219]
	v_lshlrev_b64 v[158:159], 8, v[218:219]
	s_waitcnt lgkmcnt(0)
	v_add_f32_e32 v156, v182, v183
	v_mov_b32_e32 v157, v156
	s_nop 1
	v_permlane32_swap_b32_e32 v157, v156
	v_lshl_add_u64 v[152:153], s[24:25], 0, v[152:153]
	v_cvt_pk_bf16_f32 v177, v154, v155
	v_cvt_pk_bf16_f32 v178, v178, v179
	v_cvt_pk_bf16_f32 v179, v180, v181
	v_lshl_add_u64 v[154:155], v[210:211], 1, v[152:153]
	v_lshl_add_u64 v[152:153], s[26:27], 0, v[158:159]
	global_store_dwordx4 v[154:155], v[176:179], off
	s_and_saveexec_b64 s[72:73], s[6:7]
	s_cbranch_execz .LBB0_698
	s_lshl_b32 s74, s19, 3
	s_ashr_i32 s75, s74, 31
	s_waitcnt lgkmcnt(0)
	v_add_f32_e32 v158, v156, v157
	v_lshl_add_u64 v[156:157], s[74:75], 2, v[152:153]
	s_lshl_b32 s50, s37, 2
	v_lshl_add_u64 v[156:157], v[156:157], 0, s[50:51]
	global_store_dword v[156:157], v158, off
.LBB0_698:
	s_or_b64 exec, exec, s[72:73]
	s_waitcnt vmcnt(11)
	v_pk_add_f32 v[150:151], v[30:31], v[150:151]
	v_pk_add_f32 v[148:149], v[28:29], v[148:149]
	v_pk_add_f32 v[158:159], v[24:25], v[144:145]
	v_mul_f32_e32 v144, v149, v149
	v_mul_f32_e32 v145, v151, v151
	v_fmac_f32_e32 v144, v148, v148
	v_fmac_f32_e32 v145, v150, v150
	v_add_f32_e32 v144, v144, v145
	v_mul_f32_e32 v145, v159, v159
	s_waitcnt lgkmcnt(0)
	v_pk_add_f32 v[156:157], v[26:27], v[146:147]
	v_fmac_f32_e32 v145, v158, v158
	v_add_f32_e32 v144, v144, v145
	v_mul_f32_e32 v145, v157, v157
	v_fmac_f32_e32 v145, v156, v156
	v_add_f32_e32 v144, v145, v144
	v_mov_b32_e32 v145, v144
	s_nop 1
	v_permlane16_swap_b32_e32 v145, v144
	v_cvt_pk_bf16_f32 v146, v148, v149
	v_cvt_pk_bf16_f32 v147, v150, v151
	v_cvt_pk_bf16_f32 v148, v158, v159
	v_cvt_pk_bf16_f32 v149, v156, v157
	s_waitcnt lgkmcnt(0)
	v_add_f32_e32 v144, v144, v145
	v_mov_b32_e32 v145, v144
	s_nop 1
	v_permlane32_swap_b32_e32 v145, v144
	global_store_dwordx4 v[154:155], v[146:149], off offset:256
	s_and_saveexec_b64 s[72:73], s[6:7]
	s_cbranch_execz .LBB0_700
	s_lshl_b32 s74, s19, 3
	s_ashr_i32 s75, s74, 31
	s_waitcnt lgkmcnt(0)
	v_add_f32_e32 v146, v144, v145
	v_lshl_add_u64 v[144:145], s[74:75], 2, v[152:153]
	s_lshl_b32 s50, s37, 2
	v_lshl_add_u64 v[144:145], v[144:145], 0, s[50:51]
	global_store_dword v[144:145], v146, off offset:16
.LBB0_700:
	s_or_b64 exec, exec, s[72:73]
	s_waitcnt vmcnt(10)
	v_pk_add_f32 v[146:147], v[38:39], v[174:175]
	v_pk_add_f32 v[148:149], v[36:37], v[172:173]
	v_mul_f32_e32 v151, v147, v147
	v_mul_f32_e32 v150, v149, v149
	v_pk_add_f32 v[152:153], v[32:33], v[168:169]
	v_fmac_f32_e32 v150, v148, v148
	v_fmac_f32_e32 v151, v146, v146
	v_add_f32_e32 v150, v150, v151
	v_mul_f32_e32 v151, v153, v153
	v_pk_add_f32 v[156:157], v[34:35], v[170:171]
	v_fmac_f32_e32 v151, v152, v152
	v_add_f32_e32 v150, v150, v151
	v_mul_f32_e32 v151, v157, v157
	v_fmac_f32_e32 v151, v156, v156
	v_add_f32_e32 v158, v151, v150
	v_mov_b32_e32 v159, v158
	s_nop 1
	v_permlane16_swap_b32_e32 v159, v158
	v_cvt_pk_bf16_f32 v150, v148, v149
	v_ashrrev_i32_e32 v217, 31, v216
	s_waitcnt lgkmcnt(0)
	v_lshlrev_b64 v[144:145], 12, v[216:217]
	v_lshlrev_b64 v[154:155], 8, v[216:217]
	s_waitcnt lgkmcnt(0)
	v_add_f32_e32 v148, v158, v159
	v_mov_b32_e32 v149, v148
	s_nop 1
	v_permlane32_swap_b32_e32 v149, v148
	v_lshl_add_u64 v[144:145], s[24:25], 0, v[144:145]
	v_cvt_pk_bf16_f32 v151, v146, v147
	v_cvt_pk_bf16_f32 v152, v152, v153
	v_cvt_pk_bf16_f32 v153, v156, v157
	v_lshl_add_u64 v[146:147], v[210:211], 1, v[144:145]
	v_lshl_add_u64 v[144:145], s[26:27], 0, v[154:155]
	global_store_dwordx4 v[146:147], v[150:153], off
	s_and_saveexec_b64 s[72:73], s[6:7]
	s_cbranch_execz .LBB0_702
	s_lshl_b32 s74, s19, 3
	s_ashr_i32 s75, s74, 31
	s_waitcnt lgkmcnt(0)
	v_add_f32_e32 v150, v148, v149
	v_lshl_add_u64 v[148:149], s[74:75], 2, v[144:145]
	s_lshl_b32 s50, s37, 2
	v_lshl_add_u64 v[148:149], v[148:149], 0, s[50:51]
	global_store_dword v[148:149], v150, off
.LBB0_702:
	s_or_b64 exec, exec, s[72:73]
	s_waitcnt vmcnt(9)
	v_pk_add_f32 v[142:143], v[14:15], v[142:143]
	v_pk_add_f32 v[140:141], v[12:13], v[140:141]
	v_pk_add_f32 v[150:151], v[8:9], v[136:137]
	v_mul_f32_e32 v136, v141, v141
	v_mul_f32_e32 v137, v143, v143
	v_fmac_f32_e32 v136, v140, v140
	v_fmac_f32_e32 v137, v142, v142
	v_add_f32_e32 v136, v136, v137
	v_mul_f32_e32 v137, v151, v151
	s_waitcnt lgkmcnt(0)
	v_pk_add_f32 v[148:149], v[10:11], v[138:139]
	v_fmac_f32_e32 v137, v150, v150
	v_add_f32_e32 v136, v136, v137
	v_mul_f32_e32 v137, v149, v149
	v_fmac_f32_e32 v137, v148, v148
	v_add_f32_e32 v136, v137, v136
	v_mov_b32_e32 v137, v136
	s_nop 1
	v_permlane16_swap_b32_e32 v137, v136
	v_cvt_pk_bf16_f32 v138, v140, v141
	v_cvt_pk_bf16_f32 v139, v142, v143
	v_cvt_pk_bf16_f32 v140, v150, v151
	v_cvt_pk_bf16_f32 v141, v148, v149
	s_waitcnt lgkmcnt(0)
	v_add_f32_e32 v136, v136, v137
	v_mov_b32_e32 v137, v136
	s_nop 1
	v_permlane32_swap_b32_e32 v137, v136
	global_store_dwordx4 v[146:147], v[138:141], off offset:256
	s_and_saveexec_b64 s[72:73], s[6:7]
	s_cbranch_execz .LBB0_704
	s_lshl_b32 s74, s19, 3
	s_ashr_i32 s75, s74, 31
	s_waitcnt lgkmcnt(0)
	v_add_f32_e32 v138, v136, v137
	v_lshl_add_u64 v[136:137], s[74:75], 2, v[144:145]
	s_lshl_b32 s50, s37, 2
	v_lshl_add_u64 v[136:137], v[136:137], 0, s[50:51]
	global_store_dword v[136:137], v138, off offset:16
.LBB0_704:
	s_or_b64 exec, exec, s[72:73]
	s_waitcnt vmcnt(8)
	v_pk_add_f32 v[138:139], v[22:23], v[166:167]
	v_pk_add_f32 v[140:141], v[20:21], v[164:165]
	v_mul_f32_e32 v143, v139, v139
	v_mul_f32_e32 v142, v141, v141
	v_pk_add_f32 v[144:145], v[16:17], v[160:161]
	v_fmac_f32_e32 v142, v140, v140
	v_fmac_f32_e32 v143, v138, v138
	v_add_f32_e32 v142, v142, v143
	v_mul_f32_e32 v143, v145, v145
	v_pk_add_f32 v[148:149], v[18:19], v[162:163]
	v_fmac_f32_e32 v143, v144, v144
	v_add_f32_e32 v142, v142, v143
	v_mul_f32_e32 v143, v149, v149
	v_fmac_f32_e32 v143, v148, v148
	v_add_f32_e32 v150, v143, v142
	v_mov_b32_e32 v151, v150
	s_nop 1
	v_permlane16_swap_b32_e32 v151, v150
	v_cvt_pk_bf16_f32 v142, v140, v141
	v_ashrrev_i32_e32 v215, 31, v214
	s_waitcnt lgkmcnt(0)
	v_lshlrev_b64 v[136:137], 12, v[214:215]
	v_lshlrev_b64 v[146:147], 8, v[214:215]
	s_waitcnt lgkmcnt(0)
	v_add_f32_e32 v140, v150, v151
	v_mov_b32_e32 v141, v140
	s_nop 1
	v_permlane32_swap_b32_e32 v141, v140
	v_lshl_add_u64 v[136:137], s[24:25], 0, v[136:137]
	v_cvt_pk_bf16_f32 v143, v138, v139
	v_cvt_pk_bf16_f32 v144, v144, v145
	v_cvt_pk_bf16_f32 v145, v148, v149
	v_lshl_add_u64 v[138:139], v[210:211], 1, v[136:137]
	v_lshl_add_u64 v[136:137], s[26:27], 0, v[146:147]
	global_store_dwordx4 v[138:139], v[142:145], off
	s_and_saveexec_b64 s[72:73], s[6:7]
	s_cbranch_execz .LBB0_706
	s_lshl_b32 s74, s19, 3
	s_ashr_i32 s75, s74, 31
	s_waitcnt lgkmcnt(0)
	v_add_f32_e32 v142, v140, v141
	v_lshl_add_u64 v[140:141], s[74:75], 2, v[136:137]
	s_lshl_b32 s50, s37, 2
	v_lshl_add_u64 v[140:141], v[140:141], 0, s[50:51]
	global_store_dword v[140:141], v142, off
.LBB0_706:
	s_or_b64 exec, exec, s[72:73]
	s_waitcnt vmcnt(7)
	v_pk_add_f32 v[134:135], v[6:7], v[134:135]
	v_pk_add_f32 v[132:133], v[4:5], v[132:133]
	v_pk_add_f32 v[142:143], v[0:1], v[128:129]
	v_mul_f32_e32 v128, v133, v133
	v_mul_f32_e32 v129, v135, v135
	v_fmac_f32_e32 v128, v132, v132
	v_fmac_f32_e32 v129, v134, v134
	v_add_f32_e32 v128, v128, v129
	v_mul_f32_e32 v129, v143, v143
	s_waitcnt lgkmcnt(0)
	v_pk_add_f32 v[140:141], v[2:3], v[130:131]
	v_fmac_f32_e32 v129, v142, v142
	v_add_f32_e32 v128, v128, v129
	v_mul_f32_e32 v129, v141, v141
	v_fmac_f32_e32 v129, v140, v140
	v_add_f32_e32 v128, v129, v128
	v_mov_b32_e32 v129, v128
	s_nop 1
	v_permlane16_swap_b32_e32 v129, v128
	v_cvt_pk_bf16_f32 v130, v132, v133
	v_cvt_pk_bf16_f32 v131, v134, v135
	v_cvt_pk_bf16_f32 v132, v142, v143
	v_cvt_pk_bf16_f32 v133, v140, v141
	s_waitcnt lgkmcnt(0)
	v_add_f32_e32 v128, v128, v129
	v_mov_b32_e32 v129, v128
	s_nop 1
	v_permlane32_swap_b32_e32 v129, v128
	global_store_dwordx4 v[138:139], v[130:133], off offset:256
	s_and_saveexec_b64 s[72:73], s[6:7]
	s_cbranch_execz .LBB0_708
	s_lshl_b32 s74, s19, 3
	s_ashr_i32 s75, s74, 31
	s_waitcnt lgkmcnt(0)
	v_add_f32_e32 v130, v128, v129
	v_lshl_add_u64 v[128:129], s[74:75], 2, v[136:137]
	s_lshl_b32 s50, s37, 2
	v_lshl_add_u64 v[128:129], v[128:129], 0, s[50:51]
	global_store_dword v[128:129], v130, off offset:16
